# spread exp/sum/pack VALU evenly over the MFMA gaps of the diff-attn tile loop
# speedup vs baseline: 1.0025x; 1.0025x over previous
; #define LAS __attribute__((address_space(3)))
; #define A_VLOAD(dst, d) do { const LAS char* vb_ = vbase + ((d) >> 1) * AVS + ((d) & 1) * 64; \
;         _Pragma("unroll") for (int ks = 0; ks < 4; ++ks) { const s16x4 vl_ = vtr(vb_ + (16 * ks) * AVP), vh_ = vtr(vb_ + (16 * ks + 8) * AVP); \
;             dst[ks] = (bf16x8){vl_[0], vl_[1], vl_[2], vl_[3], vh_[0], vh_[1], vh_[2], vh_[3]}; } } while (0)
; __device__ __forceinline__ void attn_unit_A(const AttnP& P, int u, LAS char* lds) {
;     ...
;         const LAS char* vbase = lds + bcur + 2 * AKS + vrow * AVP + vcolb;
;     ...
;         bf16x8 vfa[4], vfb[4];
;         A_VLOAD(vfa, 0);
;         __builtin_amdgcn_sched_barrier(0);
;         float sacc = 0.f;
; #pragma unroll
;         for (int r = 0; r < 16; ++r) { sa0[r] = __builtin_amdgcn_exp2f(sa0[r]); sa1[r] = __builtin_amdgcn_exp2f(sa1[r]); sacc += sa0[r] + sa1[r]; }
.Latt1_e_same:
	v_add_u32_e32 v192, s29, v174
	v_add_u32_e32 v235, s26, v182
	s_cmp_eq_u32 s30, 1
	s_cbranch_scc1 .Latt1_e_near
	ds_read_b128 v[184:187], v192
	ds_read_b128 v[188:191], v192 offset:4608
	ds_read_b128 v[222:225], v192 offset:32
	ds_read_b128 v[226:229], v192 offset:4640
	ds_read_b128 v[230:233], v192 offset:64
	ds_read_b128 v[244:247], v192 offset:4672
	ds_read_b128 v[248:251], v192 offset:96
	v_exp_f32_e32 v206, v206
	v_exp_f32_e32 v207, v207
	v_exp_f32_e32 v208, v208
	v_exp_f32_e32 v209, v209
	s_waitcnt lgkmcnt(6)
	v_mfma_f32_32x32x16_bf16 v[96:111], v[184:187], v[140:143], v[80:95]
	ds_read_b128 v[184:187], v192 offset:4704
	v_exp_f32_e32 v210, v210
	v_exp_f32_e32 v211, v211
	v_add_f32_e32 v179, v179, v206
	v_add_f32_e32 v202, v202, v207
	s_waitcnt lgkmcnt(6)
	v_mfma_f32_32x32x16_bf16 v[112:127], v[188:191], v[140:143], v[80:95]
	ds_read_b64_tr_b16 v[188:189], v235 offset:18432
	ds_read_b64_tr_b16 v[190:191], v235 offset:19968
	v_exp_f32_e32 v212, v212
	v_exp_f32_e32 v213, v213
	v_add_f32_e32 v179, v179, v208
	v_add_f32_e32 v202, v202, v209
	s_branch .Latt1_e_join
.Latt1_e_near:
	v_add_u32_e32 v238, s35, v183
	s_add_i32 s0, 0, 0x1f800
	v_add_u32_e32 v96, 0x40, v238
	v_med3_i32 v96, v96, s87, v240
	v_lshl_add_u32 v96, v96, 2, s0
	v_add_u32_e32 v97, 0x41, v238
	v_med3_i32 v97, v97, s87, v240
	v_lshl_add_u32 v97, v97, 2, s0
	v_add_u32_e32 v98, 0x42, v238
	v_med3_i32 v98, v98, s87, v240
	v_lshl_add_u32 v98, v98, 2, s0
	v_add_u32_e32 v99, 0x43, v238
	v_med3_i32 v99, v99, s87, v240
	v_lshl_add_u32 v99, v99, 2, s0
	v_add_u32_e32 v100, 0x48, v238
	v_med3_i32 v100, v100, s87, v240
	v_lshl_add_u32 v100, v100, 2, s0
	v_add_u32_e32 v101, 0x49, v238
	v_med3_i32 v101, v101, s87, v240
	v_lshl_add_u32 v101, v101, 2, s0
	v_add_u32_e32 v102, 0x4a, v238
	v_med3_i32 v102, v102, s87, v240
	v_lshl_add_u32 v102, v102, 2, s0
	v_add_u32_e32 v103, 0x4b, v238
	v_med3_i32 v103, v103, s87, v240
	v_lshl_add_u32 v103, v103, 2, s0
	v_add_u32_e32 v104, 0x50, v238
	v_med3_i32 v104, v104, s87, v240
	v_lshl_add_u32 v104, v104, 2, s0
	v_add_u32_e32 v105, 0x51, v238
	v_med3_i32 v105, v105, s87, v240
	v_lshl_add_u32 v105, v105, 2, s0
	v_add_u32_e32 v106, 0x52, v238
	v_med3_i32 v106, v106, s87, v240
	v_lshl_add_u32 v106, v106, 2, s0
	v_add_u32_e32 v107, 0x53, v238
	v_med3_i32 v107, v107, s87, v240
	v_lshl_add_u32 v107, v107, 2, s0
	v_add_u32_e32 v108, 0x58, v238
	v_med3_i32 v108, v108, s87, v240
	v_lshl_add_u32 v108, v108, 2, s0
	v_add_u32_e32 v109, 0x59, v238
	v_med3_i32 v109, v109, s87, v240
	v_lshl_add_u32 v109, v109, 2, s0
	v_add_u32_e32 v110, 0x5a, v238
	v_med3_i32 v110, v110, s87, v240
	v_lshl_add_u32 v110, v110, 2, s0
	v_add_u32_e32 v111, 0x5b, v238
	v_med3_i32 v111, v111, s87, v240
	v_lshl_add_u32 v111, v111, 2, s0
	ds_read_b32 v96, v96 offset:512
	ds_read_b32 v97, v97 offset:512
	ds_read_b32 v98, v98 offset:512
	ds_read_b32 v99, v99 offset:512
	ds_read_b32 v100, v100 offset:512
	ds_read_b32 v101, v101 offset:512
	ds_read_b32 v102, v102 offset:512
	ds_read_b32 v103, v103 offset:512
	ds_read_b32 v104, v104 offset:512
	ds_read_b32 v105, v105 offset:512
	ds_read_b32 v106, v106 offset:512
	ds_read_b32 v107, v107 offset:512
	ds_read_b32 v108, v108 offset:512
	ds_read_b32 v109, v109 offset:512
	ds_read_b32 v110, v110 offset:512
	ds_read_b32 v111, v111 offset:512
	v_add_u32_e32 v112, 0x60, v238
	v_med3_i32 v112, v112, s87, v240
	v_lshl_add_u32 v112, v112, 2, s0
	v_add_u32_e32 v113, 0x61, v238
	v_med3_i32 v113, v113, s87, v240
	v_lshl_add_u32 v113, v113, 2, s0
	v_add_u32_e32 v114, 0x62, v238
	v_med3_i32 v114, v114, s87, v240
	v_lshl_add_u32 v114, v114, 2, s0
	v_add_u32_e32 v115, 0x63, v238
	v_med3_i32 v115, v115, s87, v240
	v_lshl_add_u32 v115, v115, 2, s0
	v_add_u32_e32 v116, 0x68, v238
	v_med3_i32 v116, v116, s87, v240
	v_lshl_add_u32 v116, v116, 2, s0
	v_add_u32_e32 v117, 0x69, v238
	v_med3_i32 v117, v117, s87, v240
	v_lshl_add_u32 v117, v117, 2, s0
	v_add_u32_e32 v118, 0x6a, v238
	v_med3_i32 v118, v118, s87, v240
	v_lshl_add_u32 v118, v118, 2, s0
	v_add_u32_e32 v119, 0x6b, v238
	v_med3_i32 v119, v119, s87, v240
	v_lshl_add_u32 v119, v119, 2, s0
	v_add_u32_e32 v120, 0x70, v238
	v_med3_i32 v120, v120, s87, v240
	v_lshl_add_u32 v120, v120, 2, s0
	v_add_u32_e32 v121, 0x71, v238
	v_med3_i32 v121, v121, s87, v240
	v_lshl_add_u32 v121, v121, 2, s0
	v_add_u32_e32 v122, 0x72, v238
	v_med3_i32 v122, v122, s87, v240
	v_lshl_add_u32 v122, v122, 2, s0
	v_add_u32_e32 v123, 0x73, v238
	v_med3_i32 v123, v123, s87, v240
	v_lshl_add_u32 v123, v123, 2, s0
	v_add_u32_e32 v124, 0x78, v238
	v_med3_i32 v124, v124, s87, v240
	v_lshl_add_u32 v124, v124, 2, s0
	v_add_u32_e32 v125, 0x79, v238
	v_med3_i32 v125, v125, s87, v240
	v_lshl_add_u32 v125, v125, 2, s0
	v_add_u32_e32 v126, 0x7a, v238
	v_med3_i32 v126, v126, s87, v240
	v_lshl_add_u32 v126, v126, 2, s0
	v_add_u32_e32 v127, 0x7b, v238
	v_med3_i32 v127, v127, s87, v240
	v_lshl_add_u32 v127, v127, 2, s0
	ds_read_b32 v112, v112 offset:512
	ds_read_b32 v113, v113 offset:512
	ds_read_b32 v114, v114 offset:512
	ds_read_b32 v115, v115 offset:512
	ds_read_b32 v116, v116 offset:512
	ds_read_b32 v117, v117 offset:512
	ds_read_b32 v118, v118 offset:512
	ds_read_b32 v119, v119 offset:512
	ds_read_b32 v120, v120 offset:512
	ds_read_b32 v121, v121 offset:512
	ds_read_b32 v122, v122 offset:512
	ds_read_b32 v123, v123 offset:512
	ds_read_b32 v124, v124 offset:512
	ds_read_b32 v125, v125 offset:512
	ds_read_b32 v126, v126 offset:512
	ds_read_b32 v127, v127 offset:512
	s_waitcnt lgkmcnt(0)
; #define LAS __attribute__((address_space(3)))
; __device__ __forceinline__ unsigned cvtpk(float lo, float hi) { f32x2_t v = {lo, hi}; bf16x2_t b = __builtin_convertvector(v, bf16x2_t); return __builtin_bit_cast(unsigned, b); }
; #define A_VLOAD(dst, d) do { const LAS char* vb_ = vbase + ((d) >> 1) * AVS + ((d) & 1) * 64; \
;         _Pragma("unroll") for (int ks = 0; ks < 4; ++ks) { const s16x4 vl_ = vtr(vb_ + (16 * ks) * AVP), vh_ = vtr(vb_ + (16 * ks + 8) * AVP); \
;             dst[ks] = (bf16x8){vl_[0], vl_[1], vl_[2], vl_[3], vh_[0], vh_[1], vh_[2], vh_[3]}; } } while (0)
; #define A_VMMA(src, d) do { _Pragma("unroll") for (int ks = 0; ks < 4; ++ks) o[d] = __builtin_amdgcn_mfma_f32_32x32x16_bf16(src[ks], pf[ks], o[d], 0, 0, 0); } while (0)
; __device__ __forceinline__ void attn_unit_A(const AttnP& P, int u, LAS char* lds) {
;     ...
;         const LAS char* vbase = lds + bcur + 2 * AKS + vrow * AVP + vcolb;
;     ...
;         bf16x8 vfa[4], vfb[4];
;         A_VLOAD(vfa, 0);
;         __builtin_amdgcn_sched_barrier(0);
;         float sacc = 0.f;
; #pragma unroll
;         for (int r = 0; r < 16; ++r) { sa0[r] = __builtin_amdgcn_exp2f(sa0[r]); sa1[r] = __builtin_amdgcn_exp2f(sa1[r]); sacc += sa0[r] + sa1[r]; }
;         lrun += sacc;
;         bf16x8 pf[4];
;         { u32x4 a;
;           a.x = cvtpk(sa0[0], sa0[1]); a.y = cvtpk(sa0[2], sa0[3]); a.z = cvtpk(sa0[4], sa0[5]); a.w = cvtpk(sa0[6], sa0[7]); pf[0] = __builtin_bit_cast(bf16x8, a);
;           a.x = cvtpk(sa0[8], sa0[9]); a.y = cvtpk(sa0[10], sa0[11]); a.z = cvtpk(sa0[12], sa0[13]); a.w = cvtpk(sa0[14], sa0[15]); pf[1] = __builtin_bit_cast(bf16x8, a);
;           a.x = cvtpk(sa1[0], sa1[1]); a.y = cvtpk(sa1[2], sa1[3]); a.z = cvtpk(sa1[4], sa1[5]); a.w = cvtpk(sa1[6], sa1[7]); pf[2] = __builtin_bit_cast(bf16x8, a);
;           a.x = cvtpk(sa1[8], sa1[9]); a.y = cvtpk(sa1[10], sa1[11]); a.z = cvtpk(sa1[12], sa1[13]); a.w = cvtpk(sa1[14], sa1[15]); pf[3] = __builtin_bit_cast(bf16x8, a); }
;         __builtin_amdgcn_sched_barrier(0);
;         A_VLOAD(vfb, 1);
;         __builtin_amdgcn_sched_barrier(0);
;         A_VMMA(vfa, 0);
;         A_VLOAD(vfa, 2);
;         __builtin_amdgcn_sched_barrier(0);
;         A_VMMA(vfb, 1);
;         A_VLOAD(vfb, 3);
;         __builtin_amdgcn_sched_barrier(0);
;         A_VMMA(vfa, 2);
;         __builtin_amdgcn_sched_barrier(0);
;         A_VMMA(vfb, 3);
	v_add_f32_e32 v96, v96, v80
	v_add_f32_e32 v97, v97, v80
	v_add_f32_e32 v98, v98, v80
	v_add_f32_e32 v99, v99, v80
	v_add_f32_e32 v100, v100, v80
	v_add_f32_e32 v101, v101, v80
	v_add_f32_e32 v102, v102, v80
	v_add_f32_e32 v103, v103, v80
	v_add_f32_e32 v104, v104, v80
	v_add_f32_e32 v105, v105, v80
	v_add_f32_e32 v106, v106, v80
	v_add_f32_e32 v107, v107, v80
	v_add_f32_e32 v108, v108, v80
	v_add_f32_e32 v109, v109, v80
	v_add_f32_e32 v110, v110, v80
	v_add_f32_e32 v111, v111, v80
	v_add_f32_e32 v112, v112, v80
	v_add_f32_e32 v113, v113, v80
	v_add_f32_e32 v114, v114, v80
	v_add_f32_e32 v115, v115, v80
	v_add_f32_e32 v116, v116, v80
	v_add_f32_e32 v117, v117, v80
	v_add_f32_e32 v118, v118, v80
	v_add_f32_e32 v119, v119, v80
	v_add_f32_e32 v120, v120, v80
	v_add_f32_e32 v121, v121, v80
	v_add_f32_e32 v122, v122, v80
	v_add_f32_e32 v123, v123, v80
	v_add_f32_e32 v124, v124, v80
	v_add_f32_e32 v125, v125, v80
	v_add_f32_e32 v126, v126, v80
	v_add_f32_e32 v127, v127, v80
	ds_read_b128 v[184:187], v192
	ds_read_b128 v[188:191], v192 offset:4608
	ds_read_b128 v[222:225], v192 offset:32
	ds_read_b128 v[226:229], v192 offset:4640
	ds_read_b128 v[230:233], v192 offset:64
	ds_read_b128 v[244:247], v192 offset:4672
	ds_read_b128 v[248:251], v192 offset:96
	v_exp_f32_e32 v206, v206
	v_exp_f32_e32 v207, v207
	v_exp_f32_e32 v208, v208
	v_exp_f32_e32 v209, v209
	s_waitcnt lgkmcnt(6)
	v_mfma_f32_32x32x16_bf16 v[96:111], v[184:187], v[140:143], v[96:111]
	ds_read_b128 v[184:187], v192 offset:4704
	v_exp_f32_e32 v210, v210
	v_exp_f32_e32 v211, v211
	v_add_f32_e32 v179, v179, v206
	v_add_f32_e32 v202, v202, v207
	s_waitcnt lgkmcnt(6)
	v_mfma_f32_32x32x16_bf16 v[112:127], v[188:191], v[140:143], v[112:127]
	ds_read_b64_tr_b16 v[188:189], v235 offset:18432
	ds_read_b64_tr_b16 v[190:191], v235 offset:19968
	v_exp_f32_e32 v212, v212
	v_exp_f32_e32 v213, v213
	v_add_f32_e32 v179, v179, v208
	v_add_f32_e32 v202, v202, v209
.Latt1_e_join:
	s_waitcnt lgkmcnt(7)
	v_mfma_f32_32x32x16_bf16 v[96:111], v[222:225], v[136:139], v[96:111]
	ds_read_b64_tr_b16 v[222:223], v235 offset:18496
	ds_read_b64_tr_b16 v[224:225], v235 offset:20032
	v_add_f32_e32 v179, v179, v210
	v_add_f32_e32 v202, v202, v211
	v_add_f32_e32 v179, v179, v212
	v_add_f32_e32 v202, v202, v213
	v_exp_f32_e32 v214, v214
	s_waitcnt lgkmcnt(8)
	v_mfma_f32_32x32x16_bf16 v[112:127], v[226:229], v[136:139], v[112:127]
	ds_read_b64_tr_b16 v[226:227], v235 offset:30720
	ds_read_b64_tr_b16 v[228:229], v235 offset:32256
	v_cvt_pk_bf16_f32 v206, v206, v207
	v_cvt_pk_bf16_f32 v207, v208, v209
	v_cvt_pk_bf16_f32 v208, v210, v211
	v_cvt_pk_bf16_f32 v209, v212, v213
	v_exp_f32_e32 v215, v215
	s_waitcnt lgkmcnt(9)
	v_mfma_f32_32x32x16_bf16 v[96:111], v[230:233], v[132:135], v[96:111]
	ds_read_b64_tr_b16 v[230:231], v235 offset:30784
	ds_read_b64_tr_b16 v[232:233], v235 offset:32320
	v_exp_f32_e32 v216, v216
	v_exp_f32_e32 v217, v217
	v_exp_f32_e32 v218, v218
	s_waitcnt lgkmcnt(10)
	v_mfma_f32_32x32x16_bf16 v[112:127], v[244:247], v[132:135], v[112:127]
	ds_read_b64_tr_b16 v[244:245], v235 offset:21504
	ds_read_b64_tr_b16 v[246:247], v235 offset:23040
	v_exp_f32_e32 v219, v219
	v_exp_f32_e32 v220, v220
	v_exp_f32_e32 v221, v221
	s_waitcnt lgkmcnt(11)
	v_mfma_f32_32x32x16_bf16 v[96:111], v[248:251], v[128:131], v[96:111]
	ds_read_b64_tr_b16 v[248:249], v235 offset:21568
	ds_read_b64_tr_b16 v[250:251], v235 offset:23104
	v_add_f32_e32 v179, v179, v214
	v_add_f32_e32 v202, v202, v215
	v_add_f32_e32 v179, v179, v216
	v_add_f32_e32 v202, v202, v217
	v_add_f32_e32 v179, v179, v218
	v_add_f32_e32 v202, v202, v219
	s_waitcnt lgkmcnt(12)
	v_mfma_f32_32x32x16_bf16 v[112:127], v[184:187], v[128:131], v[112:127]
	ds_read_b64_tr_b16 v[184:185], v235 offset:33792
	ds_read_b64_tr_b16 v[186:187], v235 offset:35328
	v_add_f32_e32 v179, v179, v220
	v_add_f32_e32 v202, v202, v221
	v_cvt_pk_bf16_f32 v210, v214, v215
	v_cvt_pk_bf16_f32 v211, v216, v217
	v_cvt_pk_bf16_f32 v212, v218, v219
	v_cvt_pk_bf16_f32 v213, v220, v221
	s_waitcnt lgkmcnt(12)
	v_mfma_f32_32x32x16_bf16 v[64:79], v[188:191], v[206:209], v[64:79]
	ds_read_b64_tr_b16 v[188:189], v235 offset:33856
	ds_read_b64_tr_b16 v[190:191], v235 offset:35392
	v_exp_f32_e32 v0, v0
	v_exp_f32_e32 v1, v1
	v_exp_f32_e32 v2, v2
	s_waitcnt lgkmcnt(12)
	v_mfma_f32_32x32x16_bf16 v[48:63], v[222:225], v[206:209], v[48:63]
	ds_read_b64_tr_b16 v[222:223], v235 offset:24576
	ds_read_b64_tr_b16 v[224:225], v235 offset:26112
	v_exp_f32_e32 v3, v3
	v_exp_f32_e32 v4, v4
	v_exp_f32_e32 v5, v5
	s_waitcnt lgkmcnt(12)
	v_mfma_f32_32x32x16_bf16 v[32:47], v[226:229], v[206:209], v[32:47]
	ds_read_b64_tr_b16 v[226:227], v235 offset:24640
	ds_read_b64_tr_b16 v[228:229], v235 offset:26176
	v_exp_f32_e32 v6, v6
	v_exp_f32_e32 v7, v7
	v_add_f32_e32 v179, v179, v0
	v_add_f32_e32 v202, v202, v1
	s_waitcnt lgkmcnt(12)
	v_mfma_f32_32x32x16_bf16 v[16:31], v[230:233], v[206:209], v[16:31]
	ds_read_b64_tr_b16 v[230:231], v235 offset:36864
	ds_read_b64_tr_b16 v[232:233], v235 offset:38400
	v_add_f32_e32 v179, v179, v2
	v_add_f32_e32 v202, v202, v3
	v_add_f32_e32 v179, v179, v4
	v_add_f32_e32 v202, v202, v5
	v_add_f32_e32 v179, v179, v6
	v_add_f32_e32 v202, v202, v7
	s_waitcnt lgkmcnt(12)
	v_mfma_f32_32x32x16_bf16 v[64:79], v[244:247], v[210:213], v[64:79]
	ds_read_b64_tr_b16 v[244:245], v235 offset:36928
	ds_read_b64_tr_b16 v[246:247], v235 offset:38464
	v_cvt_pk_bf16_f32 v214, v0, v1
	v_cvt_pk_bf16_f32 v215, v2, v3
	v_cvt_pk_bf16_f32 v216, v4, v5
	v_cvt_pk_bf16_f32 v217, v6, v7
	v_exp_f32_e32 v8, v8
	s_waitcnt lgkmcnt(12)
; __device__ __forceinline__ void attn_unit_A(const AttnP& P, int u, LAS char* lds) {
;     ...
;         if (more) { A_WRITE(bnext); if (t + 2 < nt) A_ISSUE(t + 2); }
;         int clsn = clsk;
;         if (more) { clsn = A_CLS(t + 1);
;             if (clsn != clsk) { const float dc = A_CVAL(clsn) - A_CVAL(clsk); clsk = clsn;
; #pragma unroll
;                 for (int r = 0; r < 16; ++r) negc[r] += dc; } }
;     ...
;         const LAS char* vbase = lds + bcur + 2 * AKS + vrow * AVP + vcolb;
;     ...
;         bf16x8 vfa[4], vfb[4];
;         A_VLOAD(vfa, 0);
;         __builtin_amdgcn_sched_barrier(0);
;         float sacc = 0.f;
; #pragma unroll
;         for (int r = 0; r < 16; ++r) { sa0[r] = __builtin_amdgcn_exp2f(sa0[r]); sa1[r] = __builtin_amdgcn_exp2f(sa1[r]); sacc += sa0[r] + sa1[r]; }
;         lrun += sacc;
;         bf16x8 pf[4];
;         { u32x4 a;
;           a.x = cvtpk(sa0[0], sa0[1]); a.y = cvtpk(sa0[2], sa0[3]); a.z = cvtpk(sa0[4], sa0[5]); a.w = cvtpk(sa0[6], sa0[7]); pf[0] = __builtin_bit_cast(bf16x8, a);
;           a.x = cvtpk(sa0[8], sa0[9]); a.y = cvtpk(sa0[10], sa0[11]); a.z = cvtpk(sa0[12], sa0[13]); a.w = cvtpk(sa0[14], sa0[15]); pf[1] = __builtin_bit_cast(bf16x8, a);
;           a.x = cvtpk(sa1[0], sa1[1]); a.y = cvtpk(sa1[2], sa1[3]); a.z = cvtpk(sa1[4], sa1[5]); a.w = cvtpk(sa1[6], sa1[7]); pf[2] = __builtin_bit_cast(bf16x8, a);
;           a.x = cvtpk(sa1[8], sa1[9]); a.y = cvtpk(sa1[10], sa1[11]); a.z = cvtpk(sa1[12], sa1[13]); a.w = cvtpk(sa1[14], sa1[15]); pf[3] = __builtin_bit_cast(bf16x8, a); }
;         __builtin_amdgcn_sched_barrier(0);
;         A_VLOAD(vfb, 1);
;         __builtin_amdgcn_sched_barrier(0);
;         A_VMMA(vfa, 0);
;         A_VLOAD(vfa, 2);
;         __builtin_amdgcn_sched_barrier(0);
;         A_VMMA(vfb, 1);
;         A_VLOAD(vfb, 3);
;         __builtin_amdgcn_sched_barrier(0);
;         A_VMMA(vfa, 2);
;         __builtin_amdgcn_sched_barrier(0);
;         A_VMMA(vfb, 3);
;     ...
;         __builtin_amdgcn_sched_barrier(0); A_BAR(); A_QKBLK();
;     ...
;         if (more) {
;             if (clsn == 1) A_NEAR(sa0, sa1, t + 1);
;             float mx_; A_ROWMAX(sa0, sa1, mx_);
;             if (__any(mx_ > 8.0f)) { const float dl = fmaxf(mx_, 0.f); const float f_ = __builtin_amdgcn_exp2f(-dl); lrun *= f_;
; #pragma unroll
;                 for (int r = 0; r < 16; ++r) { sa0[r] -= dl; sa1[r] -= dl; negc[r] -= dl; }
; #pragma unroll
	v_mfma_f32_32x32x16_bf16 v[48:63], v[248:251], v[210:213], v[48:63]
	ds_read_b64_tr_b16 v[248:249], v235 offset:27648
	ds_read_b64_tr_b16 v[250:251], v235 offset:29184
	v_exp_f32_e32 v9, v9
	v_exp_f32_e32 v10, v10
	v_exp_f32_e32 v11, v11
	s_waitcnt lgkmcnt(12)
	v_mfma_f32_32x32x16_bf16 v[32:47], v[184:187], v[210:213], v[32:47]
	ds_read_b64_tr_b16 v[184:185], v235 offset:27712
	ds_read_b64_tr_b16 v[186:187], v235 offset:29248
	v_exp_f32_e32 v12, v12
	v_exp_f32_e32 v13, v13
	v_exp_f32_e32 v14, v14
	s_waitcnt lgkmcnt(12)
	v_mfma_f32_32x32x16_bf16 v[16:31], v[188:191], v[210:213], v[16:31]
	ds_read_b64_tr_b16 v[188:189], v235 offset:39936
	ds_read_b64_tr_b16 v[190:191], v235 offset:41472
	v_exp_f32_e32 v15, v15
	v_add_f32_e32 v179, v179, v8
	v_add_f32_e32 v202, v202, v9
	v_add_f32_e32 v179, v179, v10
	v_add_f32_e32 v202, v202, v11
	s_waitcnt lgkmcnt(12)
	v_mfma_f32_32x32x16_bf16 v[64:79], v[222:225], v[214:217], v[64:79]
	ds_read_b64_tr_b16 v[222:223], v235 offset:40000
	ds_read_b64_tr_b16 v[224:225], v235 offset:41536
	v_add_f32_e32 v179, v179, v12
	v_add_f32_e32 v202, v202, v13
	v_add_f32_e32 v179, v179, v14
	v_add_f32_e32 v202, v202, v15
	v_max3_f32 v243, v96, v97, v98
	s_waitcnt lgkmcnt(12)
	v_mfma_f32_32x32x16_bf16 v[48:63], v[226:229], v[214:217], v[48:63]
	v_cvt_pk_bf16_f32 v218, v8, v9
	v_cvt_pk_bf16_f32 v219, v10, v11
	v_cvt_pk_bf16_f32 v220, v12, v13
	v_cvt_pk_bf16_f32 v221, v14, v15
	v_max3_f32 v239, v112, v113, v114
	v_max3_f32 v243, v243, v99, v100
	s_waitcnt lgkmcnt(10)
	v_mfma_f32_32x32x16_bf16 v[32:47], v[230:233], v[214:217], v[32:47]
	v_max3_f32 v239, v239, v115, v116
	v_max3_f32 v243, v243, v101, v102
	v_max3_f32 v239, v239, v117, v118
	v_max3_f32 v243, v243, v103, v104
	v_max3_f32 v239, v239, v119, v120
	v_max3_f32 v243, v243, v105, v106
	v_max3_f32 v239, v239, v121, v122
	v_max3_f32 v243, v243, v107, v108
	v_max3_f32 v239, v239, v123, v124
	v_max3_f32 v243, v243, v109, v110
	v_max3_f32 v239, v239, v125, v126
	v_max_f32_e32 v243, v243, v111
	v_max_f32_e32 v239, v239, v127
	v_max_f32_e32 v243, v243, v239
	s_waitcnt lgkmcnt(8)
	v_mfma_f32_32x32x16_bf16 v[16:31], v[244:247], v[214:217], v[16:31]
	s_waitcnt vmcnt(0)
	v_add3_u32 v238, s38, v178, v160
	v_add3_u32 v239, s38, v180, v160
	ds_write_b128 v238, v[156:159]
	ds_write_b128 v238, v[152:155] offset:9216
	s_waitcnt lgkmcnt(8)
	v_mfma_f32_32x32x16_bf16 v[64:79], v[248:251], v[218:221], v[64:79]
	ds_write_b128 v239, v[148:151] offset:18432
	ds_write_b128 v239, v[144:147] offset:30720
	v_mov_b32_e32 v239, v243
	s_min_i32 s0, s31, 0xf80
	v_add_u32_e32 v238, s0, v181
	v_min_i32_e32 v238, 0x100f, v238
	s_waitcnt lgkmcnt(8)
	v_mfma_f32_32x32x16_bf16 v[48:63], v[184:187], v[218:221], v[48:63]
	v_permlane32_swap_b32_e32 v243, v239
	v_mad_i64_i32 v[192:193], s[0:1], v238, s51, v[162:163]
	global_load_dwordx4 v[156:159], v[192:193], off offset:1024
	global_load_dwordx4 v[152:155], v[192:193], off offset:1152
	s_waitcnt lgkmcnt(6)
	v_mfma_f32_32x32x16_bf16 v[32:47], v[188:191], v[218:221], v[32:47]
	global_load_dwordx4 v[148:151], v[192:193], off offset:2048
	global_load_dwordx4 v[144:147], v[192:193], off offset:2176
	v_max_f32_e32 v243, v243, v239
	s_waitcnt lgkmcnt(4)
	v_mfma_f32_32x32x16_bf16 v[16:31], v[222:225], v[218:221], v[16:31]
	s_mov_b32 s39, s30
	s_mov_b32 s26, s29
	s_mov_b32 s29, s38
	s_add_i32 s0, s38, 0xa800
	s_cmp_lg_u32 s0, 0x1f800
	s_cselect_b32 s38, s0, 0
	s_mov_b32 s35, s31
	v_cmp_lt_f32_e32 vcc, s10, v243
	s_cbranch_vccz .Latt1_e_noresc
; __device__ __forceinline__ void attn_unit_A(const AttnP& P, int u, LAS char* lds) {
;     ...
;             float mx_; A_ROWMAX(sa0, sa1, mx_);
;             if (__any(mx_ > 8.0f)) { const float dl = fmaxf(mx_, 0.f); const float f_ = __builtin_amdgcn_exp2f(-dl); lrun *= f_;
; #pragma unroll
;                 for (int r = 0; r < 16; ++r) { sa0[r] -= dl; sa1[r] -= dl; negc[r] -= dl; }
; #pragma unroll
;                 for (int d = 0; d < 4; ++d)
; #pragma unroll
;                     for (int r = 0; r < 16; ++r) o[d][r] *= f_; }
	s_nop 11
	v_max_f32_e32 v243, 0, v243
	v_exp_f32_e64 v192, -v243
	v_sub_f32_e32 v80, v80, v243
	v_sub_f32_e32 v81, v81, v243
	v_sub_f32_e32 v82, v82, v243
	v_sub_f32_e32 v83, v83, v243
	v_sub_f32_e32 v84, v84, v243
	v_sub_f32_e32 v85, v85, v243
	v_sub_f32_e32 v86, v86, v243
	v_sub_f32_e32 v87, v87, v243
	v_sub_f32_e32 v88, v88, v243
	v_sub_f32_e32 v89, v89, v243
	v_sub_f32_e32 v90, v90, v243
	v_sub_f32_e32 v91, v91, v243
	v_sub_f32_e32 v92, v92, v243
	v_sub_f32_e32 v93, v93, v243
	v_sub_f32_e32 v94, v94, v243
	v_sub_f32_e32 v95, v95, v243
	v_sub_f32_e32 v96, v96, v243
	v_sub_f32_e32 v97, v97, v243
	v_sub_f32_e32 v98, v98, v243
	v_sub_f32_e32 v99, v99, v243
	v_sub_f32_e32 v100, v100, v243
	v_sub_f32_e32 v101, v101, v243
	v_sub_f32_e32 v102, v102, v243
	v_sub_f32_e32 v103, v103, v243
	v_sub_f32_e32 v104, v104, v243
	v_sub_f32_e32 v105, v105, v243
	v_sub_f32_e32 v106, v106, v243
	v_sub_f32_e32 v107, v107, v243
	v_sub_f32_e32 v108, v108, v243
	v_sub_f32_e32 v109, v109, v243
	v_sub_f32_e32 v110, v110, v243
	v_sub_f32_e32 v111, v111, v243
	v_sub_f32_e32 v112, v112, v243
	v_sub_f32_e32 v113, v113, v243
	v_sub_f32_e32 v114, v114, v243
	v_sub_f32_e32 v115, v115, v243
	v_sub_f32_e32 v116, v116, v243
	v_sub_f32_e32 v117, v117, v243
	v_sub_f32_e32 v118, v118, v243
	v_sub_f32_e32 v119, v119, v243
	v_sub_f32_e32 v120, v120, v243
	v_sub_f32_e32 v121, v121, v243
	v_sub_f32_e32 v122, v122, v243
	v_sub_f32_e32 v123, v123, v243
	v_sub_f32_e32 v124, v124, v243
	v_sub_f32_e32 v125, v125, v243
	v_sub_f32_e32 v126, v126, v243
	v_sub_f32_e32 v127, v127, v243
	v_pk_mul_f32 v[64:65], v[64:65], v[192:193] op_sel_hi:[1,0]
	v_pk_mul_f32 v[66:67], v[66:67], v[192:193] op_sel_hi:[1,0]
	v_pk_mul_f32 v[68:69], v[68:69], v[192:193] op_sel_hi:[1,0]
	v_pk_mul_f32 v[70:71], v[70:71], v[192:193] op_sel_hi:[1,0]
	v_pk_mul_f32 v[72:73], v[72:73], v[192:193] op_sel_hi:[1,0]
	v_pk_mul_f32 v[74:75], v[74:75], v[192:193] op_sel_hi:[1,0]
	v_pk_mul_f32 v[76:77], v[76:77], v[192:193] op_sel_hi:[1,0]
	v_pk_mul_f32 v[78:79], v[78:79], v[192:193] op_sel_hi:[1,0]
	v_pk_mul_f32 v[48:49], v[48:49], v[192:193] op_sel_hi:[1,0]
	v_pk_mul_f32 v[50:51], v[50:51], v[192:193] op_sel_hi:[1,0]
	v_pk_mul_f32 v[52:53], v[52:53], v[192:193] op_sel_hi:[1,0]
	v_pk_mul_f32 v[54:55], v[54:55], v[192:193] op_sel_hi:[1,0]
	v_pk_mul_f32 v[56:57], v[56:57], v[192:193] op_sel_hi:[1,0]
	v_pk_mul_f32 v[58:59], v[58:59], v[192:193] op_sel_hi:[1,0]
	v_pk_mul_f32 v[60:61], v[60:61], v[192:193] op_sel_hi:[1,0]
	v_pk_mul_f32 v[62:63], v[62:63], v[192:193] op_sel_hi:[1,0]
	v_pk_mul_f32 v[32:33], v[32:33], v[192:193] op_sel_hi:[1,0]
	v_pk_mul_f32 v[34:35], v[34:35], v[192:193] op_sel_hi:[1,0]
	v_pk_mul_f32 v[36:37], v[36:37], v[192:193] op_sel_hi:[1,0]
	v_pk_mul_f32 v[38:39], v[38:39], v[192:193] op_sel_hi:[1,0]
	v_pk_mul_f32 v[40:41], v[40:41], v[192:193] op_sel_hi:[1,0]
	v_pk_mul_f32 v[42:43], v[42:43], v[192:193] op_sel_hi:[1,0]
	v_pk_mul_f32 v[44:45], v[44:45], v[192:193] op_sel_hi:[1,0]
	v_pk_mul_f32 v[46:47], v[46:47], v[192:193] op_sel_hi:[1,0]
	v_pk_mul_f32 v[16:17], v[16:17], v[192:193] op_sel_hi:[1,0]
	v_pk_mul_f32 v[18:19], v[18:19], v[192:193] op_sel_hi:[1,0]
	v_pk_mul_f32 v[20:21], v[20:21], v[192:193] op_sel_hi:[1,0]
	v_pk_mul_f32 v[22:23], v[22:23], v[192:193] op_sel_hi:[1,0]
	v_pk_mul_f32 v[24:25], v[24:25], v[192:193] op_sel_hi:[1,0]
	v_pk_mul_f32 v[26:27], v[26:27], v[192:193] op_sel_hi:[1,0]
	v_pk_mul_f32 v[28:29], v[28:29], v[192:193] op_sel_hi:[1,0]
	v_pk_mul_f32 v[30:31], v[30:31], v[192:193] op_sel_hi:[1,0]
	v_mul_f32_e32 v179, v179, v192
	v_mul_f32_e32 v202, v202, v192
	s_nop 1

; #define LAS __attribute__((address_space(3)))
; #define A_VLOAD(dst, d) do { const LAS char* vb_ = vbase + ((d) >> 1) * AVS + ((d) & 1) * 64; \
;         _Pragma("unroll") for (int ks = 0; ks < 4; ++ks) { const s16x4 vl_ = vtr(vb_ + (16 * ks) * AVP), vh_ = vtr(vb_ + (16 * ks + 8) * AVP); \
;             dst[ks] = (bf16x8){vl_[0], vl_[1], vl_[2], vl_[3], vh_[0], vh_[1], vh_[2], vh_[3]}; } } while (0)
; __device__ __forceinline__ void attn_unit_A(const AttnP& P, int u, LAS char* lds) {
;     ...
;         const LAS char* vbase = lds + bcur + 2 * AKS + vrow * AVP + vcolb;
;     ...
;         bf16x8 vfa[4], vfb[4];
;         A_VLOAD(vfa, 0);
;         __builtin_amdgcn_sched_barrier(0);
;         float sacc = 0.f;
; #pragma unroll
;         for (int r = 0; r < 16; ++r) { sa0[r] = __builtin_amdgcn_exp2f(sa0[r]); sa1[r] = __builtin_amdgcn_exp2f(sa1[r]); sacc += sa0[r] + sa1[r]; }
.Latt1_o_same:
	v_add_u32_e32 v192, s29, v174
	v_add_u32_e32 v235, s26, v182
	s_cmp_eq_u32 s30, 1
	s_cbranch_scc1 .Latt1_o_near
	ds_read_b128 v[184:187], v192
	ds_read_b128 v[188:191], v192 offset:4608
	ds_read_b128 v[222:225], v192 offset:32
	ds_read_b128 v[226:229], v192 offset:4640
	ds_read_b128 v[230:233], v192 offset:64
	ds_read_b128 v[244:247], v192 offset:4672
	ds_read_b128 v[248:251], v192 offset:96
	v_exp_f32_e32 v96, v96
	v_exp_f32_e32 v97, v97
	v_exp_f32_e32 v98, v98
	v_exp_f32_e32 v99, v99
	s_waitcnt lgkmcnt(6)
	v_mfma_f32_32x32x16_bf16 v[206:221], v[184:187], v[140:143], v[80:95]
	ds_read_b128 v[184:187], v192 offset:4704
	v_exp_f32_e32 v100, v100
	v_exp_f32_e32 v101, v101
	v_add_f32_e32 v179, v179, v96
	v_add_f32_e32 v202, v202, v97
	s_waitcnt lgkmcnt(6)
	v_mfma_f32_32x32x16_bf16 v[0:15], v[188:191], v[140:143], v[80:95]
	ds_read_b64_tr_b16 v[188:189], v235 offset:18432
	ds_read_b64_tr_b16 v[190:191], v235 offset:19968
	v_exp_f32_e32 v102, v102
	v_exp_f32_e32 v103, v103
	v_add_f32_e32 v179, v179, v98
	v_add_f32_e32 v202, v202, v99
	s_branch .Latt1_o_join
.Latt1_o_near:
	v_add_u32_e32 v238, s35, v183
	s_add_i32 s0, 0, 0x1f800
	v_add_u32_e32 v206, 0x40, v238
	v_med3_i32 v206, v206, s87, v240
	v_lshl_add_u32 v206, v206, 2, s0
	v_add_u32_e32 v207, 0x41, v238
	v_med3_i32 v207, v207, s87, v240
	v_lshl_add_u32 v207, v207, 2, s0
	v_add_u32_e32 v208, 0x42, v238
	v_med3_i32 v208, v208, s87, v240
	v_lshl_add_u32 v208, v208, 2, s0
	v_add_u32_e32 v209, 0x43, v238
	v_med3_i32 v209, v209, s87, v240
	v_lshl_add_u32 v209, v209, 2, s0
	v_add_u32_e32 v210, 0x48, v238
	v_med3_i32 v210, v210, s87, v240
	v_lshl_add_u32 v210, v210, 2, s0
	v_add_u32_e32 v211, 0x49, v238
	v_med3_i32 v211, v211, s87, v240
	v_lshl_add_u32 v211, v211, 2, s0
	v_add_u32_e32 v212, 0x4a, v238
	v_med3_i32 v212, v212, s87, v240
	v_lshl_add_u32 v212, v212, 2, s0
	v_add_u32_e32 v213, 0x4b, v238
	v_med3_i32 v213, v213, s87, v240
	v_lshl_add_u32 v213, v213, 2, s0
	v_add_u32_e32 v214, 0x50, v238
	v_med3_i32 v214, v214, s87, v240
	v_lshl_add_u32 v214, v214, 2, s0
	v_add_u32_e32 v215, 0x51, v238
	v_med3_i32 v215, v215, s87, v240
	v_lshl_add_u32 v215, v215, 2, s0
	v_add_u32_e32 v216, 0x52, v238
	v_med3_i32 v216, v216, s87, v240
	v_lshl_add_u32 v216, v216, 2, s0
	v_add_u32_e32 v217, 0x53, v238
	v_med3_i32 v217, v217, s87, v240
	v_lshl_add_u32 v217, v217, 2, s0
	v_add_u32_e32 v218, 0x58, v238
	v_med3_i32 v218, v218, s87, v240
	v_lshl_add_u32 v218, v218, 2, s0
	v_add_u32_e32 v219, 0x59, v238
	v_med3_i32 v219, v219, s87, v240
	v_lshl_add_u32 v219, v219, 2, s0
	v_add_u32_e32 v220, 0x5a, v238
	v_med3_i32 v220, v220, s87, v240
	v_lshl_add_u32 v220, v220, 2, s0
	v_add_u32_e32 v221, 0x5b, v238
	v_med3_i32 v221, v221, s87, v240
	v_lshl_add_u32 v221, v221, 2, s0
	ds_read_b32 v206, v206 offset:512
	ds_read_b32 v207, v207 offset:512
	ds_read_b32 v208, v208 offset:512
	ds_read_b32 v209, v209 offset:512
	ds_read_b32 v210, v210 offset:512
	ds_read_b32 v211, v211 offset:512
	ds_read_b32 v212, v212 offset:512
	ds_read_b32 v213, v213 offset:512
	ds_read_b32 v214, v214 offset:512
	ds_read_b32 v215, v215 offset:512
	ds_read_b32 v216, v216 offset:512
	ds_read_b32 v217, v217 offset:512
	ds_read_b32 v218, v218 offset:512
	ds_read_b32 v219, v219 offset:512
	ds_read_b32 v220, v220 offset:512
	ds_read_b32 v221, v221 offset:512
	v_add_u32_e32 v0, 0x60, v238
	v_med3_i32 v0, v0, s87, v240
	v_lshl_add_u32 v0, v0, 2, s0
	v_add_u32_e32 v1, 0x61, v238
	v_med3_i32 v1, v1, s87, v240
	v_lshl_add_u32 v1, v1, 2, s0
	v_add_u32_e32 v2, 0x62, v238
	v_med3_i32 v2, v2, s87, v240
	v_lshl_add_u32 v2, v2, 2, s0
	v_add_u32_e32 v3, 0x63, v238
	v_med3_i32 v3, v3, s87, v240
	v_lshl_add_u32 v3, v3, 2, s0
	v_add_u32_e32 v4, 0x68, v238
	v_med3_i32 v4, v4, s87, v240
	v_lshl_add_u32 v4, v4, 2, s0
	v_add_u32_e32 v5, 0x69, v238
	v_med3_i32 v5, v5, s87, v240
	v_lshl_add_u32 v5, v5, 2, s0
	v_add_u32_e32 v6, 0x6a, v238
	v_med3_i32 v6, v6, s87, v240
	v_lshl_add_u32 v6, v6, 2, s0
	v_add_u32_e32 v7, 0x6b, v238
	v_med3_i32 v7, v7, s87, v240
	v_lshl_add_u32 v7, v7, 2, s0
	v_add_u32_e32 v8, 0x70, v238
	v_med3_i32 v8, v8, s87, v240
	v_lshl_add_u32 v8, v8, 2, s0
	v_add_u32_e32 v9, 0x71, v238
	v_med3_i32 v9, v9, s87, v240
	v_lshl_add_u32 v9, v9, 2, s0
	v_add_u32_e32 v10, 0x72, v238
	v_med3_i32 v10, v10, s87, v240
	v_lshl_add_u32 v10, v10, 2, s0
	v_add_u32_e32 v11, 0x73, v238
	v_med3_i32 v11, v11, s87, v240
	v_lshl_add_u32 v11, v11, 2, s0
	v_add_u32_e32 v12, 0x78, v238
	v_med3_i32 v12, v12, s87, v240
	v_lshl_add_u32 v12, v12, 2, s0
	v_add_u32_e32 v13, 0x79, v238
	v_med3_i32 v13, v13, s87, v240
	v_lshl_add_u32 v13, v13, 2, s0
	v_add_u32_e32 v14, 0x7a, v238
	v_med3_i32 v14, v14, s87, v240
	v_lshl_add_u32 v14, v14, 2, s0
	v_add_u32_e32 v15, 0x7b, v238
	v_med3_i32 v15, v15, s87, v240
	v_lshl_add_u32 v15, v15, 2, s0
	ds_read_b32 v0, v0 offset:512
	ds_read_b32 v1, v1 offset:512
	ds_read_b32 v2, v2 offset:512
	ds_read_b32 v3, v3 offset:512
	ds_read_b32 v4, v4 offset:512
	ds_read_b32 v5, v5 offset:512
	ds_read_b32 v6, v6 offset:512
	ds_read_b32 v7, v7 offset:512
	ds_read_b32 v8, v8 offset:512
	ds_read_b32 v9, v9 offset:512
	ds_read_b32 v10, v10 offset:512
	ds_read_b32 v11, v11 offset:512
	ds_read_b32 v12, v12 offset:512
	ds_read_b32 v13, v13 offset:512
	ds_read_b32 v14, v14 offset:512
	ds_read_b32 v15, v15 offset:512
	s_waitcnt lgkmcnt(0)
; #define LAS __attribute__((address_space(3)))
; __device__ __forceinline__ unsigned cvtpk(float lo, float hi) { f32x2_t v = {lo, hi}; bf16x2_t b = __builtin_convertvector(v, bf16x2_t); return __builtin_bit_cast(unsigned, b); }
; #define A_VLOAD(dst, d) do { const LAS char* vb_ = vbase + ((d) >> 1) * AVS + ((d) & 1) * 64; \
;         _Pragma("unroll") for (int ks = 0; ks < 4; ++ks) { const s16x4 vl_ = vtr(vb_ + (16 * ks) * AVP), vh_ = vtr(vb_ + (16 * ks + 8) * AVP); \
;             dst[ks] = (bf16x8){vl_[0], vl_[1], vl_[2], vl_[3], vh_[0], vh_[1], vh_[2], vh_[3]}; } } while (0)
; #define A_VMMA(src, d) do { _Pragma("unroll") for (int ks = 0; ks < 4; ++ks) o[d] = __builtin_amdgcn_mfma_f32_32x32x16_bf16(src[ks], pf[ks], o[d], 0, 0, 0); } while (0)
; __device__ __forceinline__ void attn_unit_A(const AttnP& P, int u, LAS char* lds) {
;     ...
;         const LAS char* vbase = lds + bcur + 2 * AKS + vrow * AVP + vcolb;
;     ...
;         bf16x8 vfa[4], vfb[4];
;         A_VLOAD(vfa, 0);
;         __builtin_amdgcn_sched_barrier(0);
;         float sacc = 0.f;
; #pragma unroll
;         for (int r = 0; r < 16; ++r) { sa0[r] = __builtin_amdgcn_exp2f(sa0[r]); sa1[r] = __builtin_amdgcn_exp2f(sa1[r]); sacc += sa0[r] + sa1[r]; }
;         lrun += sacc;
;         bf16x8 pf[4];
;         { u32x4 a;
;           a.x = cvtpk(sa0[0], sa0[1]); a.y = cvtpk(sa0[2], sa0[3]); a.z = cvtpk(sa0[4], sa0[5]); a.w = cvtpk(sa0[6], sa0[7]); pf[0] = __builtin_bit_cast(bf16x8, a);
;           a.x = cvtpk(sa0[8], sa0[9]); a.y = cvtpk(sa0[10], sa0[11]); a.z = cvtpk(sa0[12], sa0[13]); a.w = cvtpk(sa0[14], sa0[15]); pf[1] = __builtin_bit_cast(bf16x8, a);
;           a.x = cvtpk(sa1[0], sa1[1]); a.y = cvtpk(sa1[2], sa1[3]); a.z = cvtpk(sa1[4], sa1[5]); a.w = cvtpk(sa1[6], sa1[7]); pf[2] = __builtin_bit_cast(bf16x8, a);
;           a.x = cvtpk(sa1[8], sa1[9]); a.y = cvtpk(sa1[10], sa1[11]); a.z = cvtpk(sa1[12], sa1[13]); a.w = cvtpk(sa1[14], sa1[15]); pf[3] = __builtin_bit_cast(bf16x8, a); }
;         __builtin_amdgcn_sched_barrier(0);
;         A_VLOAD(vfb, 1);
;         __builtin_amdgcn_sched_barrier(0);
;         A_VMMA(vfa, 0);
;         A_VLOAD(vfa, 2);
;         __builtin_amdgcn_sched_barrier(0);
;         A_VMMA(vfb, 1);
;         A_VLOAD(vfb, 3);
;         __builtin_amdgcn_sched_barrier(0);
;         A_VMMA(vfa, 2);
;         __builtin_amdgcn_sched_barrier(0);
;         A_VMMA(vfb, 3);
	v_add_f32_e32 v206, v206, v80
	v_add_f32_e32 v207, v207, v80
	v_add_f32_e32 v208, v208, v80
	v_add_f32_e32 v209, v209, v80
	v_add_f32_e32 v210, v210, v80
	v_add_f32_e32 v211, v211, v80
	v_add_f32_e32 v212, v212, v80
	v_add_f32_e32 v213, v213, v80
	v_add_f32_e32 v214, v214, v80
	v_add_f32_e32 v215, v215, v80
	v_add_f32_e32 v216, v216, v80
	v_add_f32_e32 v217, v217, v80
	v_add_f32_e32 v218, v218, v80
	v_add_f32_e32 v219, v219, v80
	v_add_f32_e32 v220, v220, v80
	v_add_f32_e32 v221, v221, v80
	v_add_f32_e32 v0, v0, v80
	v_add_f32_e32 v1, v1, v80
	v_add_f32_e32 v2, v2, v80
	v_add_f32_e32 v3, v3, v80
	v_add_f32_e32 v4, v4, v80
	v_add_f32_e32 v5, v5, v80
	v_add_f32_e32 v6, v6, v80
	v_add_f32_e32 v7, v7, v80
	v_add_f32_e32 v8, v8, v80
	v_add_f32_e32 v9, v9, v80
	v_add_f32_e32 v10, v10, v80
	v_add_f32_e32 v11, v11, v80
	v_add_f32_e32 v12, v12, v80
	v_add_f32_e32 v13, v13, v80
	v_add_f32_e32 v14, v14, v80
	v_add_f32_e32 v15, v15, v80
	ds_read_b128 v[184:187], v192
	ds_read_b128 v[188:191], v192 offset:4608
	ds_read_b128 v[222:225], v192 offset:32
	ds_read_b128 v[226:229], v192 offset:4640
	ds_read_b128 v[230:233], v192 offset:64
	ds_read_b128 v[244:247], v192 offset:4672
	ds_read_b128 v[248:251], v192 offset:96
	v_exp_f32_e32 v96, v96
	v_exp_f32_e32 v97, v97
	v_exp_f32_e32 v98, v98
	v_exp_f32_e32 v99, v99
	s_waitcnt lgkmcnt(6)
	v_mfma_f32_32x32x16_bf16 v[206:221], v[184:187], v[140:143], v[206:221]
	ds_read_b128 v[184:187], v192 offset:4704
	v_exp_f32_e32 v100, v100
	v_exp_f32_e32 v101, v101
	v_add_f32_e32 v179, v179, v96
	v_add_f32_e32 v202, v202, v97
	s_waitcnt lgkmcnt(6)
	v_mfma_f32_32x32x16_bf16 v[0:15], v[188:191], v[140:143], v[0:15]
	ds_read_b64_tr_b16 v[188:189], v235 offset:18432
	ds_read_b64_tr_b16 v[190:191], v235 offset:19968
	v_exp_f32_e32 v102, v102
	v_exp_f32_e32 v103, v103
	v_add_f32_e32 v179, v179, v98
	v_add_f32_e32 v202, v202, v99
.Latt1_o_join:
	s_waitcnt lgkmcnt(7)
	v_mfma_f32_32x32x16_bf16 v[206:221], v[222:225], v[136:139], v[206:221]
	ds_read_b64_tr_b16 v[222:223], v235 offset:18496
	ds_read_b64_tr_b16 v[224:225], v235 offset:20032
	v_add_f32_e32 v179, v179, v100
	v_add_f32_e32 v202, v202, v101
	v_add_f32_e32 v179, v179, v102
	v_add_f32_e32 v202, v202, v103
	v_exp_f32_e32 v104, v104
	s_waitcnt lgkmcnt(8)
	v_mfma_f32_32x32x16_bf16 v[0:15], v[226:229], v[136:139], v[0:15]
	ds_read_b64_tr_b16 v[226:227], v235 offset:30720
	ds_read_b64_tr_b16 v[228:229], v235 offset:32256
	v_cvt_pk_bf16_f32 v96, v96, v97
	v_cvt_pk_bf16_f32 v97, v98, v99
	v_cvt_pk_bf16_f32 v98, v100, v101
	v_cvt_pk_bf16_f32 v99, v102, v103
	v_exp_f32_e32 v105, v105
	s_waitcnt lgkmcnt(9)
	v_mfma_f32_32x32x16_bf16 v[206:221], v[230:233], v[132:135], v[206:221]
	ds_read_b64_tr_b16 v[230:231], v235 offset:30784
	ds_read_b64_tr_b16 v[232:233], v235 offset:32320
	v_exp_f32_e32 v106, v106
	v_exp_f32_e32 v107, v107
	v_exp_f32_e32 v108, v108
	s_waitcnt lgkmcnt(10)
	v_mfma_f32_32x32x16_bf16 v[0:15], v[244:247], v[132:135], v[0:15]
	ds_read_b64_tr_b16 v[244:245], v235 offset:21504
	ds_read_b64_tr_b16 v[246:247], v235 offset:23040
	v_exp_f32_e32 v109, v109
	v_exp_f32_e32 v110, v110
	v_exp_f32_e32 v111, v111
	s_waitcnt lgkmcnt(11)
	v_mfma_f32_32x32x16_bf16 v[206:221], v[248:251], v[128:131], v[206:221]
	ds_read_b64_tr_b16 v[248:249], v235 offset:21568
	ds_read_b64_tr_b16 v[250:251], v235 offset:23104
	v_add_f32_e32 v179, v179, v104
	v_add_f32_e32 v202, v202, v105
	v_add_f32_e32 v179, v179, v106
	v_add_f32_e32 v202, v202, v107
	v_add_f32_e32 v179, v179, v108
	v_add_f32_e32 v202, v202, v109
	s_waitcnt lgkmcnt(12)
	v_mfma_f32_32x32x16_bf16 v[0:15], v[184:187], v[128:131], v[0:15]
	ds_read_b64_tr_b16 v[184:185], v235 offset:33792
	ds_read_b64_tr_b16 v[186:187], v235 offset:35328
	v_add_f32_e32 v179, v179, v110
	v_add_f32_e32 v202, v202, v111
	v_cvt_pk_bf16_f32 v100, v104, v105
	v_cvt_pk_bf16_f32 v101, v106, v107
	v_cvt_pk_bf16_f32 v102, v108, v109
	v_cvt_pk_bf16_f32 v103, v110, v111
	s_waitcnt lgkmcnt(12)
	v_mfma_f32_32x32x16_bf16 v[64:79], v[188:191], v[96:99], v[64:79]
	ds_read_b64_tr_b16 v[188:189], v235 offset:33856
	ds_read_b64_tr_b16 v[190:191], v235 offset:35392
	v_exp_f32_e32 v112, v112
	v_exp_f32_e32 v113, v113
	v_exp_f32_e32 v114, v114
	s_waitcnt lgkmcnt(12)
	v_mfma_f32_32x32x16_bf16 v[48:63], v[222:225], v[96:99], v[48:63]
	ds_read_b64_tr_b16 v[222:223], v235 offset:24576
	ds_read_b64_tr_b16 v[224:225], v235 offset:26112
	v_exp_f32_e32 v115, v115
	v_exp_f32_e32 v116, v116
	v_exp_f32_e32 v117, v117
	s_waitcnt lgkmcnt(12)
	v_mfma_f32_32x32x16_bf16 v[32:47], v[226:229], v[96:99], v[32:47]
	ds_read_b64_tr_b16 v[226:227], v235 offset:24640
	ds_read_b64_tr_b16 v[228:229], v235 offset:26176
	v_exp_f32_e32 v118, v118
	v_exp_f32_e32 v119, v119
	v_add_f32_e32 v179, v179, v112
	v_add_f32_e32 v202, v202, v113
	s_waitcnt lgkmcnt(12)
	v_mfma_f32_32x32x16_bf16 v[16:31], v[230:233], v[96:99], v[16:31]
	ds_read_b64_tr_b16 v[230:231], v235 offset:36864
	ds_read_b64_tr_b16 v[232:233], v235 offset:38400
	v_add_f32_e32 v179, v179, v114
	v_add_f32_e32 v202, v202, v115
	v_add_f32_e32 v179, v179, v116
	v_add_f32_e32 v202, v202, v117
	v_add_f32_e32 v179, v179, v118
	v_add_f32_e32 v202, v202, v119
	s_waitcnt lgkmcnt(12)
	v_mfma_f32_32x32x16_bf16 v[64:79], v[244:247], v[100:103], v[64:79]
	ds_read_b64_tr_b16 v[244:245], v235 offset:36928
	ds_read_b64_tr_b16 v[246:247], v235 offset:38464
	v_cvt_pk_bf16_f32 v104, v112, v113
	v_cvt_pk_bf16_f32 v105, v114, v115
	v_cvt_pk_bf16_f32 v106, v116, v117
	v_cvt_pk_bf16_f32 v107, v118, v119
	v_exp_f32_e32 v120, v120
	s_waitcnt lgkmcnt(12)
; __device__ __forceinline__ void attn_unit_A(const AttnP& P, int u, LAS char* lds) {
;     ...
;         if (more) { A_WRITE(bnext); if (t + 2 < nt) A_ISSUE(t + 2); }
;         int clsn = clsk;
;         if (more) { clsn = A_CLS(t + 1);
;             if (clsn != clsk) { const float dc = A_CVAL(clsn) - A_CVAL(clsk); clsk = clsn;
; #pragma unroll
;                 for (int r = 0; r < 16; ++r) negc[r] += dc; } }
;     ...
;         const LAS char* vbase = lds + bcur + 2 * AKS + vrow * AVP + vcolb;
;     ...
;         bf16x8 vfa[4], vfb[4];
;         A_VLOAD(vfa, 0);
;         __builtin_amdgcn_sched_barrier(0);
;         float sacc = 0.f;
; #pragma unroll
;         for (int r = 0; r < 16; ++r) { sa0[r] = __builtin_amdgcn_exp2f(sa0[r]); sa1[r] = __builtin_amdgcn_exp2f(sa1[r]); sacc += sa0[r] + sa1[r]; }
;         lrun += sacc;
;         bf16x8 pf[4];
;         { u32x4 a;
;           a.x = cvtpk(sa0[0], sa0[1]); a.y = cvtpk(sa0[2], sa0[3]); a.z = cvtpk(sa0[4], sa0[5]); a.w = cvtpk(sa0[6], sa0[7]); pf[0] = __builtin_bit_cast(bf16x8, a);
;           a.x = cvtpk(sa0[8], sa0[9]); a.y = cvtpk(sa0[10], sa0[11]); a.z = cvtpk(sa0[12], sa0[13]); a.w = cvtpk(sa0[14], sa0[15]); pf[1] = __builtin_bit_cast(bf16x8, a);
;           a.x = cvtpk(sa1[0], sa1[1]); a.y = cvtpk(sa1[2], sa1[3]); a.z = cvtpk(sa1[4], sa1[5]); a.w = cvtpk(sa1[6], sa1[7]); pf[2] = __builtin_bit_cast(bf16x8, a);
;           a.x = cvtpk(sa1[8], sa1[9]); a.y = cvtpk(sa1[10], sa1[11]); a.z = cvtpk(sa1[12], sa1[13]); a.w = cvtpk(sa1[14], sa1[15]); pf[3] = __builtin_bit_cast(bf16x8, a); }
;         __builtin_amdgcn_sched_barrier(0);
;         A_VLOAD(vfb, 1);
;         __builtin_amdgcn_sched_barrier(0);
;         A_VMMA(vfa, 0);
;         A_VLOAD(vfa, 2);
;         __builtin_amdgcn_sched_barrier(0);
;         A_VMMA(vfb, 1);
;         A_VLOAD(vfb, 3);
;         __builtin_amdgcn_sched_barrier(0);
;         A_VMMA(vfa, 2);
;         __builtin_amdgcn_sched_barrier(0);
;         A_VMMA(vfb, 3);
;     ...
;         __builtin_amdgcn_sched_barrier(0); A_BAR(); A_QKBLK();
;     ...
;         if (more) {
;             if (clsn == 1) A_NEAR(sa0, sa1, t + 1);
;             float mx_; A_ROWMAX(sa0, sa1, mx_);
;             if (__any(mx_ > 8.0f)) { const float dl = fmaxf(mx_, 0.f); const float f_ = __builtin_amdgcn_exp2f(-dl); lrun *= f_;
; #pragma unroll
;                 for (int r = 0; r < 16; ++r) { sa0[r] -= dl; sa1[r] -= dl; negc[r] -= dl; }
; #pragma unroll
	v_mfma_f32_32x32x16_bf16 v[48:63], v[248:251], v[100:103], v[48:63]
	ds_read_b64_tr_b16 v[248:249], v235 offset:27648
	ds_read_b64_tr_b16 v[250:251], v235 offset:29184
	v_exp_f32_e32 v121, v121
	v_exp_f32_e32 v122, v122
	v_exp_f32_e32 v123, v123
	s_waitcnt lgkmcnt(12)
	v_mfma_f32_32x32x16_bf16 v[32:47], v[184:187], v[100:103], v[32:47]
	ds_read_b64_tr_b16 v[184:185], v235 offset:27712
	ds_read_b64_tr_b16 v[186:187], v235 offset:29248
	v_exp_f32_e32 v124, v124
	v_exp_f32_e32 v125, v125
	v_exp_f32_e32 v126, v126
	s_waitcnt lgkmcnt(12)
	v_mfma_f32_32x32x16_bf16 v[16:31], v[188:191], v[100:103], v[16:31]
	ds_read_b64_tr_b16 v[188:189], v235 offset:39936
	ds_read_b64_tr_b16 v[190:191], v235 offset:41472
	v_exp_f32_e32 v127, v127
	v_add_f32_e32 v179, v179, v120
	v_add_f32_e32 v202, v202, v121
	v_add_f32_e32 v179, v179, v122
	v_add_f32_e32 v202, v202, v123
	s_waitcnt lgkmcnt(12)
	v_mfma_f32_32x32x16_bf16 v[64:79], v[222:225], v[104:107], v[64:79]
	ds_read_b64_tr_b16 v[222:223], v235 offset:40000
	ds_read_b64_tr_b16 v[224:225], v235 offset:41536
	v_add_f32_e32 v179, v179, v124
	v_add_f32_e32 v202, v202, v125
	v_add_f32_e32 v179, v179, v126
	v_add_f32_e32 v202, v202, v127
	v_max3_f32 v243, v206, v207, v208
	s_waitcnt lgkmcnt(12)
	v_mfma_f32_32x32x16_bf16 v[48:63], v[226:229], v[104:107], v[48:63]
	v_cvt_pk_bf16_f32 v108, v120, v121
	v_cvt_pk_bf16_f32 v109, v122, v123
	v_cvt_pk_bf16_f32 v110, v124, v125
	v_cvt_pk_bf16_f32 v111, v126, v127
	v_max3_f32 v239, v0, v1, v2
	v_max3_f32 v243, v243, v209, v210
	s_waitcnt lgkmcnt(10)
	v_mfma_f32_32x32x16_bf16 v[32:47], v[230:233], v[104:107], v[32:47]
	v_max3_f32 v239, v239, v3, v4
	v_max3_f32 v243, v243, v211, v212
	v_max3_f32 v239, v239, v5, v6
	v_max3_f32 v243, v243, v213, v214
	v_max3_f32 v239, v239, v7, v8
	v_max3_f32 v243, v243, v215, v216
	v_max3_f32 v239, v239, v9, v10
	v_max3_f32 v243, v243, v217, v218
	v_max3_f32 v239, v239, v11, v12
	v_max3_f32 v243, v243, v219, v220
	v_max3_f32 v239, v239, v13, v14
	v_max_f32_e32 v243, v243, v221
	v_max_f32_e32 v239, v239, v15
	v_max_f32_e32 v243, v243, v239
	s_waitcnt lgkmcnt(8)
	v_mfma_f32_32x32x16_bf16 v[16:31], v[244:247], v[104:107], v[16:31]
	s_waitcnt vmcnt(0)
	v_add3_u32 v238, s38, v178, v160
	v_add3_u32 v239, s38, v180, v160
	ds_write_b128 v238, v[156:159]
	ds_write_b128 v238, v[152:155] offset:9216
	s_waitcnt lgkmcnt(8)
	v_mfma_f32_32x32x16_bf16 v[64:79], v[248:251], v[108:111], v[64:79]
	ds_write_b128 v239, v[148:151] offset:18432
	ds_write_b128 v239, v[144:147] offset:30720
	v_mov_b32_e32 v239, v243
	s_min_i32 s0, s31, 0xf80
	v_add_u32_e32 v238, s0, v181
	v_min_i32_e32 v238, 0x100f, v238
	s_waitcnt lgkmcnt(8)
	v_mfma_f32_32x32x16_bf16 v[48:63], v[184:187], v[108:111], v[48:63]
	v_permlane32_swap_b32_e32 v243, v239
	v_mad_i64_i32 v[192:193], s[0:1], v238, s51, v[162:163]
	global_load_dwordx4 v[156:159], v[192:193], off offset:1024
	global_load_dwordx4 v[152:155], v[192:193], off offset:1152
	s_waitcnt lgkmcnt(6)
	v_mfma_f32_32x32x16_bf16 v[32:47], v[188:191], v[108:111], v[32:47]
	global_load_dwordx4 v[148:151], v[192:193], off offset:2048
	global_load_dwordx4 v[144:147], v[192:193], off offset:2176
	v_max_f32_e32 v243, v243, v239
	s_waitcnt lgkmcnt(4)
	v_mfma_f32_32x32x16_bf16 v[16:31], v[222:225], v[108:111], v[16:31]
	s_mov_b32 s39, s30
	s_mov_b32 s26, s29
	s_mov_b32 s29, s38
	s_add_i32 s0, s38, 0xa800
	s_cmp_lg_u32 s0, 0x1f800
	s_cselect_b32 s38, s0, 0
	s_mov_b32 s35, s31
	v_cmp_lt_f32_e32 vcc, s10, v243
	s_cbranch_vccz .Latt1_o_noresc
	s_nop 11
	v_max_f32_e32 v243, 0, v243
	v_exp_f32_e64 v192, -v243
	v_sub_f32_e32 v80, v80, v243
	v_sub_f32_e32 v81, v81, v243
	v_sub_f32_e32 v82, v82, v243
	v_sub_f32_e32 v83, v83, v243
	v_sub_f32_e32 v84, v84, v243
	v_sub_f32_e32 v85, v85, v243
	v_sub_f32_e32 v86, v86, v243
	v_sub_f32_e32 v87, v87, v243
	v_sub_f32_e32 v88, v88, v243
	v_sub_f32_e32 v89, v89, v243
	v_sub_f32_e32 v90, v90, v243
	v_sub_f32_e32 v91, v91, v243
	v_sub_f32_e32 v92, v92, v243
	v_sub_f32_e32 v93, v93, v243
	v_sub_f32_e32 v94, v94, v243
	v_sub_f32_e32 v95, v95, v243
	v_sub_f32_e32 v206, v206, v243
	v_sub_f32_e32 v207, v207, v243
	v_sub_f32_e32 v208, v208, v243
	v_sub_f32_e32 v209, v209, v243
	v_sub_f32_e32 v210, v210, v243
	v_sub_f32_e32 v211, v211, v243
	v_sub_f32_e32 v212, v212, v243
	v_sub_f32_e32 v213, v213, v243
	v_sub_f32_e32 v214, v214, v243
	v_sub_f32_e32 v215, v215, v243
	v_sub_f32_e32 v216, v216, v243
	v_sub_f32_e32 v217, v217, v243
	v_sub_f32_e32 v218, v218, v243
	v_sub_f32_e32 v219, v219, v243
	v_sub_f32_e32 v220, v220, v243
	v_sub_f32_e32 v221, v221, v243
	v_sub_f32_e32 v0, v0, v243
	v_sub_f32_e32 v1, v1, v243
	v_sub_f32_e32 v2, v2, v243
	v_sub_f32_e32 v3, v3, v243
	v_sub_f32_e32 v4, v4, v243
	v_sub_f32_e32 v5, v5, v243
	v_sub_f32_e32 v6, v6, v243
	v_sub_f32_e32 v7, v7, v243
	v_sub_f32_e32 v8, v8, v243
	v_sub_f32_e32 v9, v9, v243
	v_sub_f32_e32 v10, v10, v243
	v_sub_f32_e32 v11, v11, v243
	v_sub_f32_e32 v12, v12, v243
	v_sub_f32_e32 v13, v13, v243
	v_sub_f32_e32 v14, v14, v243
	v_sub_f32_e32 v15, v15, v243
	v_pk_mul_f32 v[64:65], v[64:65], v[192:193] op_sel_hi:[1,0]
	v_pk_mul_f32 v[66:67], v[66:67], v[192:193] op_sel_hi:[1,0]
	v_pk_mul_f32 v[68:69], v[68:69], v[192:193] op_sel_hi:[1,0]
	v_pk_mul_f32 v[70:71], v[70:71], v[192:193] op_sel_hi:[1,0]
	v_pk_mul_f32 v[72:73], v[72:73], v[192:193] op_sel_hi:[1,0]
	v_pk_mul_f32 v[74:75], v[74:75], v[192:193] op_sel_hi:[1,0]
	v_pk_mul_f32 v[76:77], v[76:77], v[192:193] op_sel_hi:[1,0]
	v_pk_mul_f32 v[78:79], v[78:79], v[192:193] op_sel_hi:[1,0]
	v_pk_mul_f32 v[48:49], v[48:49], v[192:193] op_sel_hi:[1,0]
	v_pk_mul_f32 v[50:51], v[50:51], v[192:193] op_sel_hi:[1,0]
	v_pk_mul_f32 v[52:53], v[52:53], v[192:193] op_sel_hi:[1,0]
	v_pk_mul_f32 v[54:55], v[54:55], v[192:193] op_sel_hi:[1,0]
	v_pk_mul_f32 v[56:57], v[56:57], v[192:193] op_sel_hi:[1,0]
	v_pk_mul_f32 v[58:59], v[58:59], v[192:193] op_sel_hi:[1,0]
	v_pk_mul_f32 v[60:61], v[60:61], v[192:193] op_sel_hi:[1,0]
	v_pk_mul_f32 v[62:63], v[62:63], v[192:193] op_sel_hi:[1,0]
	v_pk_mul_f32 v[32:33], v[32:33], v[192:193] op_sel_hi:[1,0]
	v_pk_mul_f32 v[34:35], v[34:35], v[192:193] op_sel_hi:[1,0]
	v_pk_mul_f32 v[36:37], v[36:37], v[192:193] op_sel_hi:[1,0]
	v_pk_mul_f32 v[38:39], v[38:39], v[192:193] op_sel_hi:[1,0]
	v_pk_mul_f32 v[40:41], v[40:41], v[192:193] op_sel_hi:[1,0]
	v_pk_mul_f32 v[42:43], v[42:43], v[192:193] op_sel_hi:[1,0]
	v_pk_mul_f32 v[44:45], v[44:45], v[192:193] op_sel_hi:[1,0]
	v_pk_mul_f32 v[46:47], v[46:47], v[192:193] op_sel_hi:[1,0]
	v_pk_mul_f32 v[16:17], v[16:17], v[192:193] op_sel_hi:[1,0]
	v_pk_mul_f32 v[18:19], v[18:19], v[192:193] op_sel_hi:[1,0]
	v_pk_mul_f32 v[20:21], v[20:21], v[192:193] op_sel_hi:[1,0]
	v_pk_mul_f32 v[22:23], v[22:23], v[192:193] op_sel_hi:[1,0]
	v_pk_mul_f32 v[24:25], v[24:25], v[192:193] op_sel_hi:[1,0]
	v_pk_mul_f32 v[26:27], v[26:27], v[192:193] op_sel_hi:[1,0]
	v_pk_mul_f32 v[28:29], v[28:29], v[192:193] op_sel_hi:[1,0]
	v_pk_mul_f32 v[30:31], v[30:31], v[192:193] op_sel_hi:[1,0]
	v_mul_f32_e32 v179, v179, v192
	v_mul_f32_e32 v202, v202, v192
	s_nop 1

; #define LAS __attribute__((address_space(3)))
; #define A_VLOAD(dst, d) do { const LAS char* vb_ = vbase + ((d) >> 1) * AVS + ((d) & 1) * 64; \
;         _Pragma("unroll") for (int ks = 0; ks < 4; ++ks) { const s16x4 vl_ = vtr(vb_ + (16 * ks) * AVP), vh_ = vtr(vb_ + (16 * ks + 8) * AVP); \
;             dst[ks] = (bf16x8){vl_[0], vl_[1], vl_[2], vl_[3], vh_[0], vh_[1], vh_[2], vh_[3]}; } } while (0)
; __device__ __forceinline__ void attn_unit_A(const AttnP& P, int u, LAS char* lds) {
;     ...
;         const LAS char* vbase = lds + bcur + 2 * AKS + vrow * AVP + vcolb;
;     ...
;         bf16x8 vfa[4], vfb[4];
;         A_VLOAD(vfa, 0);
;         __builtin_amdgcn_sched_barrier(0);
;         float sacc = 0.f;
; #pragma unroll
;         for (int r = 0; r < 16; ++r) { sa0[r] = __builtin_amdgcn_exp2f(sa0[r]); sa1[r] = __builtin_amdgcn_exp2f(sa1[r]); sacc += sa0[r] + sa1[r]; }
.Latt2_e_same:
	v_add_u32_e32 v244, s28, v164
	v_add_u32_e32 v235, s26, v176
	s_cmp_eq_u32 s29, 1
	s_cbranch_scc1 .Latt2_e_near
	ds_read_b128 v[178:181], v244
	ds_read_b128 v[182:185], v244 offset:4608
	ds_read_b128 v[186:189], v244 offset:32
	ds_read_b128 v[190:193], v244 offset:4640
	ds_read_b128 v[222:225], v244 offset:64
	ds_read_b128 v[226:229], v244 offset:4672
	ds_read_b128 v[230:233], v244 offset:96
	v_exp_f32_e32 v206, v206
	v_exp_f32_e32 v207, v207
	v_exp_f32_e32 v208, v208
	v_exp_f32_e32 v209, v209
	s_waitcnt lgkmcnt(6)
	v_mfma_f32_32x32x16_bf16 v[96:111], v[178:181], v[140:143], v[80:95]
	ds_read_b128 v[178:181], v244 offset:4704
	v_exp_f32_e32 v210, v210
	v_exp_f32_e32 v211, v211
	v_add_f32_e32 v173, v173, v206
	v_add_f32_e32 v202, v202, v207
	s_waitcnt lgkmcnt(6)
	v_mfma_f32_32x32x16_bf16 v[112:127], v[182:185], v[140:143], v[80:95]
	ds_read_b64_tr_b16 v[182:183], v235 offset:18432
	ds_read_b64_tr_b16 v[184:185], v235 offset:19968
	v_exp_f32_e32 v212, v212
	v_exp_f32_e32 v213, v213
	v_add_f32_e32 v173, v173, v208
	v_add_f32_e32 v202, v202, v209
	s_branch .Latt2_e_join
.Latt2_e_near:
	v_add_u32_e32 v238, s31, v177
	s_add_i32 s0, 0, 0x1f800
	v_add_u32_e32 v96, 0xfffff040, v238
	v_med3_i32 v96, v96, s87, v240
	v_lshl_add_u32 v96, v96, 2, s0
	v_add_u32_e32 v97, 0xfffff041, v238
	v_med3_i32 v97, v97, s87, v240
	v_lshl_add_u32 v97, v97, 2, s0
	v_add_u32_e32 v98, 0xfffff042, v238
	v_med3_i32 v98, v98, s87, v240
	v_lshl_add_u32 v98, v98, 2, s0
	v_add_u32_e32 v99, 0xfffff043, v238
	v_med3_i32 v99, v99, s87, v240
	v_lshl_add_u32 v99, v99, 2, s0
	v_add_u32_e32 v100, 0xfffff048, v238
	v_med3_i32 v100, v100, s87, v240
	v_lshl_add_u32 v100, v100, 2, s0
	v_add_u32_e32 v101, 0xfffff049, v238
	v_med3_i32 v101, v101, s87, v240
	v_lshl_add_u32 v101, v101, 2, s0
	v_add_u32_e32 v102, 0xfffff04a, v238
	v_med3_i32 v102, v102, s87, v240
	v_lshl_add_u32 v102, v102, 2, s0
	v_add_u32_e32 v103, 0xfffff04b, v238
	v_med3_i32 v103, v103, s87, v240
	v_lshl_add_u32 v103, v103, 2, s0
	v_add_u32_e32 v104, 0xfffff050, v238
	v_med3_i32 v104, v104, s87, v240
	v_lshl_add_u32 v104, v104, 2, s0
	v_add_u32_e32 v105, 0xfffff051, v238
	v_med3_i32 v105, v105, s87, v240
	v_lshl_add_u32 v105, v105, 2, s0
	v_add_u32_e32 v106, 0xfffff052, v238
	v_med3_i32 v106, v106, s87, v240
	v_lshl_add_u32 v106, v106, 2, s0
	v_add_u32_e32 v107, 0xfffff053, v238
	v_med3_i32 v107, v107, s87, v240
	v_lshl_add_u32 v107, v107, 2, s0
	v_add_u32_e32 v108, 0xfffff058, v238
	v_med3_i32 v108, v108, s87, v240
	v_lshl_add_u32 v108, v108, 2, s0
	v_add_u32_e32 v109, 0xfffff059, v238
	v_med3_i32 v109, v109, s87, v240
	v_lshl_add_u32 v109, v109, 2, s0
	v_add_u32_e32 v110, 0xfffff05a, v238
	v_med3_i32 v110, v110, s87, v240
	v_lshl_add_u32 v110, v110, 2, s0
	v_add_u32_e32 v111, 0xfffff05b, v238
	v_med3_i32 v111, v111, s87, v240
	v_lshl_add_u32 v111, v111, 2, s0
	ds_read_b32 v96, v96 offset:512
	ds_read_b32 v97, v97 offset:512
	ds_read_b32 v98, v98 offset:512
	ds_read_b32 v99, v99 offset:512
	ds_read_b32 v100, v100 offset:512
	ds_read_b32 v101, v101 offset:512
	ds_read_b32 v102, v102 offset:512
	ds_read_b32 v103, v103 offset:512
	ds_read_b32 v104, v104 offset:512
	ds_read_b32 v105, v105 offset:512
	ds_read_b32 v106, v106 offset:512
	ds_read_b32 v107, v107 offset:512
	ds_read_b32 v108, v108 offset:512
	ds_read_b32 v109, v109 offset:512
	ds_read_b32 v110, v110 offset:512
	ds_read_b32 v111, v111 offset:512
	v_add_u32_e32 v112, 0xfffff060, v238
	v_med3_i32 v112, v112, s87, v240
	v_lshl_add_u32 v112, v112, 2, s0
	v_add_u32_e32 v113, 0xfffff061, v238
	v_med3_i32 v113, v113, s87, v240
	v_lshl_add_u32 v113, v113, 2, s0
	v_add_u32_e32 v114, 0xfffff062, v238
	v_med3_i32 v114, v114, s87, v240
	v_lshl_add_u32 v114, v114, 2, s0
	v_add_u32_e32 v115, 0xfffff063, v238
	v_med3_i32 v115, v115, s87, v240
	v_lshl_add_u32 v115, v115, 2, s0
	v_add_u32_e32 v116, 0xfffff068, v238
	v_med3_i32 v116, v116, s87, v240
	v_lshl_add_u32 v116, v116, 2, s0
	v_add_u32_e32 v117, 0xfffff069, v238
	v_med3_i32 v117, v117, s87, v240
	v_lshl_add_u32 v117, v117, 2, s0
	v_add_u32_e32 v118, 0xfffff06a, v238
	v_med3_i32 v118, v118, s87, v240
	v_lshl_add_u32 v118, v118, 2, s0
	v_add_u32_e32 v119, 0xfffff06b, v238
	v_med3_i32 v119, v119, s87, v240
	v_lshl_add_u32 v119, v119, 2, s0
	v_add_u32_e32 v120, 0xfffff070, v238
	v_med3_i32 v120, v120, s87, v240
	v_lshl_add_u32 v120, v120, 2, s0
	v_add_u32_e32 v121, 0xfffff071, v238
	v_med3_i32 v121, v121, s87, v240
	v_lshl_add_u32 v121, v121, 2, s0
	v_add_u32_e32 v122, 0xfffff072, v238
	v_med3_i32 v122, v122, s87, v240
	v_lshl_add_u32 v122, v122, 2, s0
	v_add_u32_e32 v123, 0xfffff073, v238
	v_med3_i32 v123, v123, s87, v240
	v_lshl_add_u32 v123, v123, 2, s0
	v_add_u32_e32 v124, 0xfffff078, v238
	v_med3_i32 v124, v124, s87, v240
	v_lshl_add_u32 v124, v124, 2, s0
	v_add_u32_e32 v125, 0xfffff079, v238
	v_med3_i32 v125, v125, s87, v240
	v_lshl_add_u32 v125, v125, 2, s0
	v_add_u32_e32 v126, 0xfffff07a, v238
	v_med3_i32 v126, v126, s87, v240
	v_lshl_add_u32 v126, v126, 2, s0
	v_add_u32_e32 v127, 0xfffff07b, v238
	v_med3_i32 v127, v127, s87, v240
	v_lshl_add_u32 v127, v127, 2, s0
	ds_read_b32 v112, v112 offset:512
	ds_read_b32 v113, v113 offset:512
	ds_read_b32 v114, v114 offset:512
	ds_read_b32 v115, v115 offset:512
	ds_read_b32 v116, v116 offset:512
	ds_read_b32 v117, v117 offset:512
	ds_read_b32 v118, v118 offset:512
	ds_read_b32 v119, v119 offset:512
	ds_read_b32 v120, v120 offset:512
	ds_read_b32 v121, v121 offset:512
	ds_read_b32 v122, v122 offset:512
	ds_read_b32 v123, v123 offset:512
	ds_read_b32 v124, v124 offset:512
	ds_read_b32 v125, v125 offset:512
	ds_read_b32 v126, v126 offset:512
	ds_read_b32 v127, v127 offset:512
	s_waitcnt lgkmcnt(0)
; #define LAS __attribute__((address_space(3)))
; __device__ __forceinline__ unsigned cvtpk(float lo, float hi) { f32x2_t v = {lo, hi}; bf16x2_t b = __builtin_convertvector(v, bf16x2_t); return __builtin_bit_cast(unsigned, b); }
; #define A_VLOAD(dst, d) do { const LAS char* vb_ = vbase + ((d) >> 1) * AVS + ((d) & 1) * 64; \
;         _Pragma("unroll") for (int ks = 0; ks < 4; ++ks) { const s16x4 vl_ = vtr(vb_ + (16 * ks) * AVP), vh_ = vtr(vb_ + (16 * ks + 8) * AVP); \
;             dst[ks] = (bf16x8){vl_[0], vl_[1], vl_[2], vl_[3], vh_[0], vh_[1], vh_[2], vh_[3]}; } } while (0)
; #define A_VMMA(src, d) do { _Pragma("unroll") for (int ks = 0; ks < 4; ++ks) o[d] = __builtin_amdgcn_mfma_f32_32x32x16_bf16(src[ks], pf[ks], o[d], 0, 0, 0); } while (0)
; __device__ __forceinline__ void attn_unit_A(const AttnP& P, int u, LAS char* lds) {
;     ...
;         const LAS char* vbase = lds + bcur + 2 * AKS + vrow * AVP + vcolb;
;     ...
;         bf16x8 vfa[4], vfb[4];
;         A_VLOAD(vfa, 0);
;         __builtin_amdgcn_sched_barrier(0);
;         float sacc = 0.f;
; #pragma unroll
;         for (int r = 0; r < 16; ++r) { sa0[r] = __builtin_amdgcn_exp2f(sa0[r]); sa1[r] = __builtin_amdgcn_exp2f(sa1[r]); sacc += sa0[r] + sa1[r]; }
;         lrun += sacc;
;         bf16x8 pf[4];
;         { u32x4 a;
;           a.x = cvtpk(sa0[0], sa0[1]); a.y = cvtpk(sa0[2], sa0[3]); a.z = cvtpk(sa0[4], sa0[5]); a.w = cvtpk(sa0[6], sa0[7]); pf[0] = __builtin_bit_cast(bf16x8, a);
;           a.x = cvtpk(sa0[8], sa0[9]); a.y = cvtpk(sa0[10], sa0[11]); a.z = cvtpk(sa0[12], sa0[13]); a.w = cvtpk(sa0[14], sa0[15]); pf[1] = __builtin_bit_cast(bf16x8, a);
;           a.x = cvtpk(sa1[0], sa1[1]); a.y = cvtpk(sa1[2], sa1[3]); a.z = cvtpk(sa1[4], sa1[5]); a.w = cvtpk(sa1[6], sa1[7]); pf[2] = __builtin_bit_cast(bf16x8, a);
;           a.x = cvtpk(sa1[8], sa1[9]); a.y = cvtpk(sa1[10], sa1[11]); a.z = cvtpk(sa1[12], sa1[13]); a.w = cvtpk(sa1[14], sa1[15]); pf[3] = __builtin_bit_cast(bf16x8, a); }
;         __builtin_amdgcn_sched_barrier(0);
;         A_VLOAD(vfb, 1);
;         __builtin_amdgcn_sched_barrier(0);
;         A_VMMA(vfa, 0);
;         A_VLOAD(vfa, 2);
;         __builtin_amdgcn_sched_barrier(0);
;         A_VMMA(vfb, 1);
;         A_VLOAD(vfb, 3);
;         __builtin_amdgcn_sched_barrier(0);
;         A_VMMA(vfa, 2);
;         __builtin_amdgcn_sched_barrier(0);
;         A_VMMA(vfb, 3);
	v_add_f32_e32 v96, v96, v80
	v_add_f32_e32 v97, v97, v80
	v_add_f32_e32 v98, v98, v80
	v_add_f32_e32 v99, v99, v80
	v_add_f32_e32 v100, v100, v80
	v_add_f32_e32 v101, v101, v80
	v_add_f32_e32 v102, v102, v80
	v_add_f32_e32 v103, v103, v80
	v_add_f32_e32 v104, v104, v80
	v_add_f32_e32 v105, v105, v80
	v_add_f32_e32 v106, v106, v80
	v_add_f32_e32 v107, v107, v80
	v_add_f32_e32 v108, v108, v80
	v_add_f32_e32 v109, v109, v80
	v_add_f32_e32 v110, v110, v80
	v_add_f32_e32 v111, v111, v80
	v_add_f32_e32 v112, v112, v80
	v_add_f32_e32 v113, v113, v80
	v_add_f32_e32 v114, v114, v80
	v_add_f32_e32 v115, v115, v80
	v_add_f32_e32 v116, v116, v80
	v_add_f32_e32 v117, v117, v80
	v_add_f32_e32 v118, v118, v80
	v_add_f32_e32 v119, v119, v80
	v_add_f32_e32 v120, v120, v80
	v_add_f32_e32 v121, v121, v80
	v_add_f32_e32 v122, v122, v80
	v_add_f32_e32 v123, v123, v80
	v_add_f32_e32 v124, v124, v80
	v_add_f32_e32 v125, v125, v80
	v_add_f32_e32 v126, v126, v80
	v_add_f32_e32 v127, v127, v80
	ds_read_b128 v[178:181], v244
	ds_read_b128 v[182:185], v244 offset:4608
	ds_read_b128 v[186:189], v244 offset:32
	ds_read_b128 v[190:193], v244 offset:4640
	ds_read_b128 v[222:225], v244 offset:64
	ds_read_b128 v[226:229], v244 offset:4672
	ds_read_b128 v[230:233], v244 offset:96
	v_exp_f32_e32 v206, v206
	v_exp_f32_e32 v207, v207
	v_exp_f32_e32 v208, v208
	v_exp_f32_e32 v209, v209
	s_waitcnt lgkmcnt(6)
	v_mfma_f32_32x32x16_bf16 v[96:111], v[178:181], v[140:143], v[96:111]
	ds_read_b128 v[178:181], v244 offset:4704
	v_exp_f32_e32 v210, v210
	v_exp_f32_e32 v211, v211
	v_add_f32_e32 v173, v173, v206
	v_add_f32_e32 v202, v202, v207
	s_waitcnt lgkmcnt(6)
	v_mfma_f32_32x32x16_bf16 v[112:127], v[182:185], v[140:143], v[112:127]
	ds_read_b64_tr_b16 v[182:183], v235 offset:18432
	ds_read_b64_tr_b16 v[184:185], v235 offset:19968
	v_exp_f32_e32 v212, v212
	v_exp_f32_e32 v213, v213
	v_add_f32_e32 v173, v173, v208
	v_add_f32_e32 v202, v202, v209
.Latt2_e_join:
	s_waitcnt lgkmcnt(7)
	v_mfma_f32_32x32x16_bf16 v[96:111], v[186:189], v[136:139], v[96:111]
	ds_read_b64_tr_b16 v[186:187], v235 offset:18496
	ds_read_b64_tr_b16 v[188:189], v235 offset:20032
	v_add_f32_e32 v173, v173, v210
	v_add_f32_e32 v202, v202, v211
	v_add_f32_e32 v173, v173, v212
	v_add_f32_e32 v202, v202, v213
	v_exp_f32_e32 v214, v214
	s_waitcnt lgkmcnt(8)
	v_mfma_f32_32x32x16_bf16 v[112:127], v[190:193], v[136:139], v[112:127]
	ds_read_b64_tr_b16 v[190:191], v235 offset:30720
	ds_read_b64_tr_b16 v[192:193], v235 offset:32256
	v_cvt_pk_bf16_f32 v206, v206, v207
	v_cvt_pk_bf16_f32 v207, v208, v209
	v_cvt_pk_bf16_f32 v208, v210, v211
	v_cvt_pk_bf16_f32 v209, v212, v213
	v_exp_f32_e32 v215, v215
	s_waitcnt lgkmcnt(9)
	v_mfma_f32_32x32x16_bf16 v[96:111], v[222:225], v[132:135], v[96:111]
	ds_read_b64_tr_b16 v[222:223], v235 offset:30784
	ds_read_b64_tr_b16 v[224:225], v235 offset:32320
	v_exp_f32_e32 v216, v216
	v_exp_f32_e32 v217, v217
	v_exp_f32_e32 v218, v218
	s_waitcnt lgkmcnt(10)
	v_mfma_f32_32x32x16_bf16 v[112:127], v[226:229], v[132:135], v[112:127]
	ds_read_b64_tr_b16 v[226:227], v235 offset:21504
	ds_read_b64_tr_b16 v[228:229], v235 offset:23040
	v_exp_f32_e32 v219, v219
	v_exp_f32_e32 v220, v220
	v_exp_f32_e32 v221, v221
	s_waitcnt lgkmcnt(11)
	v_mfma_f32_32x32x16_bf16 v[96:111], v[230:233], v[128:131], v[96:111]
	ds_read_b64_tr_b16 v[230:231], v235 offset:21568
	ds_read_b64_tr_b16 v[232:233], v235 offset:23104
	v_add_f32_e32 v173, v173, v214
	v_add_f32_e32 v202, v202, v215
	v_add_f32_e32 v173, v173, v216
	v_add_f32_e32 v202, v202, v217
	v_add_f32_e32 v173, v173, v218
	v_add_f32_e32 v202, v202, v219
	s_waitcnt lgkmcnt(12)
	v_mfma_f32_32x32x16_bf16 v[112:127], v[178:181], v[128:131], v[112:127]
	ds_read_b64_tr_b16 v[178:179], v235 offset:33792
	ds_read_b64_tr_b16 v[180:181], v235 offset:35328
	v_add_f32_e32 v173, v173, v220
	v_add_f32_e32 v202, v202, v221
	v_cvt_pk_bf16_f32 v210, v214, v215
	v_cvt_pk_bf16_f32 v211, v216, v217
	v_cvt_pk_bf16_f32 v212, v218, v219
	v_cvt_pk_bf16_f32 v213, v220, v221
	s_waitcnt lgkmcnt(12)
	v_mfma_f32_32x32x16_bf16 v[64:79], v[182:185], v[206:209], v[64:79]
	ds_read_b64_tr_b16 v[182:183], v235 offset:33856
	ds_read_b64_tr_b16 v[184:185], v235 offset:35392
	v_exp_f32_e32 v0, v0
	v_exp_f32_e32 v1, v1
	v_exp_f32_e32 v2, v2
	s_waitcnt lgkmcnt(12)
	v_mfma_f32_32x32x16_bf16 v[48:63], v[186:189], v[206:209], v[48:63]
	ds_read_b64_tr_b16 v[186:187], v235 offset:24576
	ds_read_b64_tr_b16 v[188:189], v235 offset:26112
	v_exp_f32_e32 v3, v3
	v_exp_f32_e32 v4, v4
	v_exp_f32_e32 v5, v5
	s_waitcnt lgkmcnt(12)
	v_mfma_f32_32x32x16_bf16 v[32:47], v[190:193], v[206:209], v[32:47]
	ds_read_b64_tr_b16 v[190:191], v235 offset:24640
	ds_read_b64_tr_b16 v[192:193], v235 offset:26176
	v_exp_f32_e32 v6, v6
	v_exp_f32_e32 v7, v7
	v_add_f32_e32 v173, v173, v0
	v_add_f32_e32 v202, v202, v1
	s_waitcnt lgkmcnt(12)
	v_mfma_f32_32x32x16_bf16 v[16:31], v[222:225], v[206:209], v[16:31]
	ds_read_b64_tr_b16 v[222:223], v235 offset:36864
	ds_read_b64_tr_b16 v[224:225], v235 offset:38400
	v_add_f32_e32 v173, v173, v2
	v_add_f32_e32 v202, v202, v3
	v_add_f32_e32 v173, v173, v4
	v_add_f32_e32 v202, v202, v5
	v_add_f32_e32 v173, v173, v6
	v_add_f32_e32 v202, v202, v7
	s_waitcnt lgkmcnt(12)
	v_mfma_f32_32x32x16_bf16 v[64:79], v[226:229], v[210:213], v[64:79]
	ds_read_b64_tr_b16 v[226:227], v235 offset:36928
	ds_read_b64_tr_b16 v[228:229], v235 offset:38464
	v_cvt_pk_bf16_f32 v214, v0, v1
	v_cvt_pk_bf16_f32 v215, v2, v3
	v_cvt_pk_bf16_f32 v216, v4, v5
	v_cvt_pk_bf16_f32 v217, v6, v7
	v_exp_f32_e32 v8, v8
	s_waitcnt lgkmcnt(12)
; __device__ __forceinline__ void attn_unit_A(const AttnP& P, int u, LAS char* lds) {
;     ...
;         if (more) { A_WRITE(bnext); if (t + 2 < nt) A_ISSUE(t + 2); }
;         int clsn = clsk;
;         if (more) { clsn = A_CLS(t + 1);
;             if (clsn != clsk) { const float dc = A_CVAL(clsn) - A_CVAL(clsk); clsk = clsn;
; #pragma unroll
;                 for (int r = 0; r < 16; ++r) negc[r] += dc; } }
;     ...
;         const LAS char* vbase = lds + bcur + 2 * AKS + vrow * AVP + vcolb;
;     ...
;         bf16x8 vfa[4], vfb[4];
;         A_VLOAD(vfa, 0);
;         __builtin_amdgcn_sched_barrier(0);
;         float sacc = 0.f;
; #pragma unroll
;         for (int r = 0; r < 16; ++r) { sa0[r] = __builtin_amdgcn_exp2f(sa0[r]); sa1[r] = __builtin_amdgcn_exp2f(sa1[r]); sacc += sa0[r] + sa1[r]; }
;         lrun += sacc;
;         bf16x8 pf[4];
;         { u32x4 a;
;           a.x = cvtpk(sa0[0], sa0[1]); a.y = cvtpk(sa0[2], sa0[3]); a.z = cvtpk(sa0[4], sa0[5]); a.w = cvtpk(sa0[6], sa0[7]); pf[0] = __builtin_bit_cast(bf16x8, a);
;           a.x = cvtpk(sa0[8], sa0[9]); a.y = cvtpk(sa0[10], sa0[11]); a.z = cvtpk(sa0[12], sa0[13]); a.w = cvtpk(sa0[14], sa0[15]); pf[1] = __builtin_bit_cast(bf16x8, a);
;           a.x = cvtpk(sa1[0], sa1[1]); a.y = cvtpk(sa1[2], sa1[3]); a.z = cvtpk(sa1[4], sa1[5]); a.w = cvtpk(sa1[6], sa1[7]); pf[2] = __builtin_bit_cast(bf16x8, a);
;           a.x = cvtpk(sa1[8], sa1[9]); a.y = cvtpk(sa1[10], sa1[11]); a.z = cvtpk(sa1[12], sa1[13]); a.w = cvtpk(sa1[14], sa1[15]); pf[3] = __builtin_bit_cast(bf16x8, a); }
;         __builtin_amdgcn_sched_barrier(0);
;         A_VLOAD(vfb, 1);
;         __builtin_amdgcn_sched_barrier(0);
;         A_VMMA(vfa, 0);
;         A_VLOAD(vfa, 2);
;         __builtin_amdgcn_sched_barrier(0);
;         A_VMMA(vfb, 1);
;         A_VLOAD(vfb, 3);
;         __builtin_amdgcn_sched_barrier(0);
;         A_VMMA(vfa, 2);
;         __builtin_amdgcn_sched_barrier(0);
;         A_VMMA(vfb, 3);
;     ...
;         __builtin_amdgcn_sched_barrier(0); A_BAR(); A_QKBLK();
;     ...
;         if (more) {
;             if (clsn == 1) A_NEAR(sa0, sa1, t + 1);
;             float mx_; A_ROWMAX(sa0, sa1, mx_);
;             if (__any(mx_ > 8.0f)) { const float dl = fmaxf(mx_, 0.f); const float f_ = __builtin_amdgcn_exp2f(-dl); lrun *= f_;
; #pragma unroll
;                 for (int r = 0; r < 16; ++r) { sa0[r] -= dl; sa1[r] -= dl; negc[r] -= dl; }
; #pragma unroll
	v_mfma_f32_32x32x16_bf16 v[48:63], v[230:233], v[210:213], v[48:63]
	ds_read_b64_tr_b16 v[230:231], v235 offset:27648
	ds_read_b64_tr_b16 v[232:233], v235 offset:29184
	v_exp_f32_e32 v9, v9
	v_exp_f32_e32 v10, v10
	v_exp_f32_e32 v11, v11
	s_waitcnt lgkmcnt(12)
	v_mfma_f32_32x32x16_bf16 v[32:47], v[178:181], v[210:213], v[32:47]
	ds_read_b64_tr_b16 v[178:179], v235 offset:27712
	ds_read_b64_tr_b16 v[180:181], v235 offset:29248
	v_exp_f32_e32 v12, v12
	v_exp_f32_e32 v13, v13
	v_exp_f32_e32 v14, v14
	s_waitcnt lgkmcnt(12)
	v_mfma_f32_32x32x16_bf16 v[16:31], v[182:185], v[210:213], v[16:31]
	ds_read_b64_tr_b16 v[182:183], v235 offset:39936
	ds_read_b64_tr_b16 v[184:185], v235 offset:41472
	v_exp_f32_e32 v15, v15
	v_add_f32_e32 v173, v173, v8
	v_add_f32_e32 v202, v202, v9
	v_add_f32_e32 v173, v173, v10
	v_add_f32_e32 v202, v202, v11
	s_waitcnt lgkmcnt(12)
	v_mfma_f32_32x32x16_bf16 v[64:79], v[186:189], v[214:217], v[64:79]
	ds_read_b64_tr_b16 v[186:187], v235 offset:40000
	ds_read_b64_tr_b16 v[188:189], v235 offset:41536
	v_add_f32_e32 v173, v173, v12
	v_add_f32_e32 v202, v202, v13
	v_add_f32_e32 v173, v173, v14
	v_add_f32_e32 v202, v202, v15
	v_max3_f32 v243, v96, v97, v98
	s_waitcnt lgkmcnt(12)
	v_mfma_f32_32x32x16_bf16 v[48:63], v[190:193], v[214:217], v[48:63]
	v_cvt_pk_bf16_f32 v218, v8, v9
	v_cvt_pk_bf16_f32 v219, v10, v11
	v_cvt_pk_bf16_f32 v220, v12, v13
	v_cvt_pk_bf16_f32 v221, v14, v15
	v_max3_f32 v239, v112, v113, v114
	v_max3_f32 v243, v243, v99, v100
	s_waitcnt lgkmcnt(10)
	v_mfma_f32_32x32x16_bf16 v[32:47], v[222:225], v[214:217], v[32:47]
	v_max3_f32 v239, v239, v115, v116
	v_max3_f32 v243, v243, v101, v102
	v_max3_f32 v239, v239, v117, v118
	v_max3_f32 v243, v243, v103, v104
	v_max3_f32 v239, v239, v119, v120
	v_max3_f32 v243, v243, v105, v106
	v_max3_f32 v239, v239, v121, v122
	v_max3_f32 v243, v243, v107, v108
	v_max3_f32 v239, v239, v123, v124
	v_max3_f32 v243, v243, v109, v110
	v_max3_f32 v239, v239, v125, v126
	v_max_f32_e32 v243, v243, v111
	v_max_f32_e32 v239, v239, v127
	v_max_f32_e32 v243, v243, v239
	s_waitcnt lgkmcnt(8)
	v_mfma_f32_32x32x16_bf16 v[16:31], v[226:229], v[214:217], v[16:31]
	s_waitcnt vmcnt(0)
	v_add3_u32 v238, s35, v172, v160
	v_add3_u32 v239, s35, v174, v160
	ds_write_b128 v238, v[156:159]
	ds_write_b128 v238, v[152:155] offset:9216
	s_waitcnt lgkmcnt(8)
	v_mfma_f32_32x32x16_bf16 v[64:79], v[230:233], v[218:221], v[64:79]
	ds_write_b128 v239, v[148:151] offset:18432
	ds_write_b128 v239, v[144:147] offset:30720
	v_mov_b32_e32 v239, v243
	s_min_i32 s0, s30, 0xf80
	v_add_u32_e32 v238, s0, v175
	v_min_i32_e32 v238, 0x100f, v238
	s_waitcnt lgkmcnt(8)
	v_mfma_f32_32x32x16_bf16 v[48:63], v[178:181], v[218:221], v[48:63]
	v_permlane32_swap_b32_e32 v243, v239
	v_mad_i64_i32 v[244:245], s[0:1], v238, s51, v[162:163]
	global_load_dwordx4 v[156:159], v[244:245], off offset:1024
	global_load_dwordx4 v[152:155], v[244:245], off offset:1152
	s_waitcnt lgkmcnt(6)
	v_mfma_f32_32x32x16_bf16 v[32:47], v[182:185], v[218:221], v[32:47]
	global_load_dwordx4 v[148:151], v[244:245], off offset:2048
	global_load_dwordx4 v[144:147], v[244:245], off offset:2176
	v_max_f32_e32 v243, v243, v239
	s_waitcnt lgkmcnt(4)
	v_mfma_f32_32x32x16_bf16 v[16:31], v[186:189], v[218:221], v[16:31]
	s_mov_b32 s34, s29
	s_mov_b32 s26, s28
	s_mov_b32 s28, s35
	s_add_i32 s0, s35, 0xa800
	s_cmp_lg_u32 s0, 0x1f800
	s_cselect_b32 s35, s0, 0
	s_mov_b32 s31, s30
	v_cmp_lt_f32_e32 vcc, s10, v243
	s_cbranch_vccz .Latt2_e_noresc
; __device__ __forceinline__ void attn_unit_A(const AttnP& P, int u, LAS char* lds) {
;     ...
;             float mx_; A_ROWMAX(sa0, sa1, mx_);
;             if (__any(mx_ > 8.0f)) { const float dl = fmaxf(mx_, 0.f); const float f_ = __builtin_amdgcn_exp2f(-dl); lrun *= f_;
; #pragma unroll
;                 for (int r = 0; r < 16; ++r) { sa0[r] -= dl; sa1[r] -= dl; negc[r] -= dl; }
; #pragma unroll
;                 for (int d = 0; d < 4; ++d)
; #pragma unroll
;                     for (int r = 0; r < 16; ++r) o[d][r] *= f_; }
	s_nop 11
	v_max_f32_e32 v243, 0, v243
	v_exp_f32_e64 v244, -v243
	v_sub_f32_e32 v80, v80, v243
	v_sub_f32_e32 v81, v81, v243
	v_sub_f32_e32 v82, v82, v243
	v_sub_f32_e32 v83, v83, v243
	v_sub_f32_e32 v84, v84, v243
	v_sub_f32_e32 v85, v85, v243
	v_sub_f32_e32 v86, v86, v243
	v_sub_f32_e32 v87, v87, v243
	v_sub_f32_e32 v88, v88, v243
	v_sub_f32_e32 v89, v89, v243
	v_sub_f32_e32 v90, v90, v243
	v_sub_f32_e32 v91, v91, v243
	v_sub_f32_e32 v92, v92, v243
	v_sub_f32_e32 v93, v93, v243
	v_sub_f32_e32 v94, v94, v243
	v_sub_f32_e32 v95, v95, v243
	v_sub_f32_e32 v96, v96, v243
	v_sub_f32_e32 v97, v97, v243
	v_sub_f32_e32 v98, v98, v243
	v_sub_f32_e32 v99, v99, v243
	v_sub_f32_e32 v100, v100, v243
	v_sub_f32_e32 v101, v101, v243
	v_sub_f32_e32 v102, v102, v243
	v_sub_f32_e32 v103, v103, v243
	v_sub_f32_e32 v104, v104, v243
	v_sub_f32_e32 v105, v105, v243
	v_sub_f32_e32 v106, v106, v243
	v_sub_f32_e32 v107, v107, v243
	v_sub_f32_e32 v108, v108, v243
	v_sub_f32_e32 v109, v109, v243
	v_sub_f32_e32 v110, v110, v243
	v_sub_f32_e32 v111, v111, v243
	v_sub_f32_e32 v112, v112, v243
	v_sub_f32_e32 v113, v113, v243
	v_sub_f32_e32 v114, v114, v243
	v_sub_f32_e32 v115, v115, v243
	v_sub_f32_e32 v116, v116, v243
	v_sub_f32_e32 v117, v117, v243
	v_sub_f32_e32 v118, v118, v243
	v_sub_f32_e32 v119, v119, v243
	v_sub_f32_e32 v120, v120, v243
	v_sub_f32_e32 v121, v121, v243
	v_sub_f32_e32 v122, v122, v243
	v_sub_f32_e32 v123, v123, v243
	v_sub_f32_e32 v124, v124, v243
	v_sub_f32_e32 v125, v125, v243
	v_sub_f32_e32 v126, v126, v243
	v_sub_f32_e32 v127, v127, v243
	v_pk_mul_f32 v[64:65], v[64:65], v[244:245] op_sel_hi:[1,0]
	v_pk_mul_f32 v[66:67], v[66:67], v[244:245] op_sel_hi:[1,0]
	v_pk_mul_f32 v[68:69], v[68:69], v[244:245] op_sel_hi:[1,0]
	v_pk_mul_f32 v[70:71], v[70:71], v[244:245] op_sel_hi:[1,0]
	v_pk_mul_f32 v[72:73], v[72:73], v[244:245] op_sel_hi:[1,0]
	v_pk_mul_f32 v[74:75], v[74:75], v[244:245] op_sel_hi:[1,0]
	v_pk_mul_f32 v[76:77], v[76:77], v[244:245] op_sel_hi:[1,0]
	v_pk_mul_f32 v[78:79], v[78:79], v[244:245] op_sel_hi:[1,0]
	v_pk_mul_f32 v[48:49], v[48:49], v[244:245] op_sel_hi:[1,0]
	v_pk_mul_f32 v[50:51], v[50:51], v[244:245] op_sel_hi:[1,0]
	v_pk_mul_f32 v[52:53], v[52:53], v[244:245] op_sel_hi:[1,0]
	v_pk_mul_f32 v[54:55], v[54:55], v[244:245] op_sel_hi:[1,0]
	v_pk_mul_f32 v[56:57], v[56:57], v[244:245] op_sel_hi:[1,0]
	v_pk_mul_f32 v[58:59], v[58:59], v[244:245] op_sel_hi:[1,0]
	v_pk_mul_f32 v[60:61], v[60:61], v[244:245] op_sel_hi:[1,0]
	v_pk_mul_f32 v[62:63], v[62:63], v[244:245] op_sel_hi:[1,0]
	v_pk_mul_f32 v[32:33], v[32:33], v[244:245] op_sel_hi:[1,0]
	v_pk_mul_f32 v[34:35], v[34:35], v[244:245] op_sel_hi:[1,0]
	v_pk_mul_f32 v[36:37], v[36:37], v[244:245] op_sel_hi:[1,0]
	v_pk_mul_f32 v[38:39], v[38:39], v[244:245] op_sel_hi:[1,0]
	v_pk_mul_f32 v[40:41], v[40:41], v[244:245] op_sel_hi:[1,0]
	v_pk_mul_f32 v[42:43], v[42:43], v[244:245] op_sel_hi:[1,0]
	v_pk_mul_f32 v[44:45], v[44:45], v[244:245] op_sel_hi:[1,0]
	v_pk_mul_f32 v[46:47], v[46:47], v[244:245] op_sel_hi:[1,0]
	v_pk_mul_f32 v[16:17], v[16:17], v[244:245] op_sel_hi:[1,0]
	v_pk_mul_f32 v[18:19], v[18:19], v[244:245] op_sel_hi:[1,0]
	v_pk_mul_f32 v[20:21], v[20:21], v[244:245] op_sel_hi:[1,0]
	v_pk_mul_f32 v[22:23], v[22:23], v[244:245] op_sel_hi:[1,0]
	v_pk_mul_f32 v[24:25], v[24:25], v[244:245] op_sel_hi:[1,0]
	v_pk_mul_f32 v[26:27], v[26:27], v[244:245] op_sel_hi:[1,0]
	v_pk_mul_f32 v[28:29], v[28:29], v[244:245] op_sel_hi:[1,0]
	v_pk_mul_f32 v[30:31], v[30:31], v[244:245] op_sel_hi:[1,0]
	v_mul_f32_e32 v173, v173, v244
	v_mul_f32_e32 v202, v202, v244
	s_nop 1

; #define LAS __attribute__((address_space(3)))
; #define A_VLOAD(dst, d) do { const LAS char* vb_ = vbase + ((d) >> 1) * AVS + ((d) & 1) * 64; \
;         _Pragma("unroll") for (int ks = 0; ks < 4; ++ks) { const s16x4 vl_ = vtr(vb_ + (16 * ks) * AVP), vh_ = vtr(vb_ + (16 * ks + 8) * AVP); \
;             dst[ks] = (bf16x8){vl_[0], vl_[1], vl_[2], vl_[3], vh_[0], vh_[1], vh_[2], vh_[3]}; } } while (0)
; __device__ __forceinline__ void attn_unit_A(const AttnP& P, int u, LAS char* lds) {
;     ...
;         const LAS char* vbase = lds + bcur + 2 * AKS + vrow * AVP + vcolb;
;     ...
;         bf16x8 vfa[4], vfb[4];
;         A_VLOAD(vfa, 0);
;         __builtin_amdgcn_sched_barrier(0);
;         float sacc = 0.f;
; #pragma unroll
;         for (int r = 0; r < 16; ++r) { sa0[r] = __builtin_amdgcn_exp2f(sa0[r]); sa1[r] = __builtin_amdgcn_exp2f(sa1[r]); sacc += sa0[r] + sa1[r]; }
.Latt2_o_same:
	v_add_u32_e32 v244, s28, v164
	v_add_u32_e32 v235, s26, v176
	s_cmp_eq_u32 s29, 1
	s_cbranch_scc1 .Latt2_o_near
	ds_read_b128 v[178:181], v244
	ds_read_b128 v[182:185], v244 offset:4608
	ds_read_b128 v[186:189], v244 offset:32
	ds_read_b128 v[190:193], v244 offset:4640
	ds_read_b128 v[222:225], v244 offset:64
	ds_read_b128 v[226:229], v244 offset:4672
	ds_read_b128 v[230:233], v244 offset:96
	v_exp_f32_e32 v96, v96
	v_exp_f32_e32 v97, v97
	v_exp_f32_e32 v98, v98
	v_exp_f32_e32 v99, v99
	s_waitcnt lgkmcnt(6)
	v_mfma_f32_32x32x16_bf16 v[206:221], v[178:181], v[140:143], v[80:95]
	ds_read_b128 v[178:181], v244 offset:4704
	v_exp_f32_e32 v100, v100
	v_exp_f32_e32 v101, v101
	v_add_f32_e32 v173, v173, v96
	v_add_f32_e32 v202, v202, v97
	s_waitcnt lgkmcnt(6)
	v_mfma_f32_32x32x16_bf16 v[0:15], v[182:185], v[140:143], v[80:95]
	ds_read_b64_tr_b16 v[182:183], v235 offset:18432
	ds_read_b64_tr_b16 v[184:185], v235 offset:19968
	v_exp_f32_e32 v102, v102
	v_exp_f32_e32 v103, v103
	v_add_f32_e32 v173, v173, v98
	v_add_f32_e32 v202, v202, v99
	s_branch .Latt2_o_join
.Latt2_o_near:
	v_add_u32_e32 v238, s31, v177
	s_add_i32 s0, 0, 0x1f800
	v_add_u32_e32 v206, 0xfffff040, v238
	v_med3_i32 v206, v206, s87, v240
	v_lshl_add_u32 v206, v206, 2, s0
	v_add_u32_e32 v207, 0xfffff041, v238
	v_med3_i32 v207, v207, s87, v240
	v_lshl_add_u32 v207, v207, 2, s0
	v_add_u32_e32 v208, 0xfffff042, v238
	v_med3_i32 v208, v208, s87, v240
	v_lshl_add_u32 v208, v208, 2, s0
	v_add_u32_e32 v209, 0xfffff043, v238
	v_med3_i32 v209, v209, s87, v240
	v_lshl_add_u32 v209, v209, 2, s0
	v_add_u32_e32 v210, 0xfffff048, v238
	v_med3_i32 v210, v210, s87, v240
	v_lshl_add_u32 v210, v210, 2, s0
	v_add_u32_e32 v211, 0xfffff049, v238
	v_med3_i32 v211, v211, s87, v240
	v_lshl_add_u32 v211, v211, 2, s0
	v_add_u32_e32 v212, 0xfffff04a, v238
	v_med3_i32 v212, v212, s87, v240
	v_lshl_add_u32 v212, v212, 2, s0
	v_add_u32_e32 v213, 0xfffff04b, v238
	v_med3_i32 v213, v213, s87, v240
	v_lshl_add_u32 v213, v213, 2, s0
	v_add_u32_e32 v214, 0xfffff050, v238
	v_med3_i32 v214, v214, s87, v240
	v_lshl_add_u32 v214, v214, 2, s0
	v_add_u32_e32 v215, 0xfffff051, v238
	v_med3_i32 v215, v215, s87, v240
	v_lshl_add_u32 v215, v215, 2, s0
	v_add_u32_e32 v216, 0xfffff052, v238
	v_med3_i32 v216, v216, s87, v240
	v_lshl_add_u32 v216, v216, 2, s0
	v_add_u32_e32 v217, 0xfffff053, v238
	v_med3_i32 v217, v217, s87, v240
	v_lshl_add_u32 v217, v217, 2, s0
	v_add_u32_e32 v218, 0xfffff058, v238
	v_med3_i32 v218, v218, s87, v240
	v_lshl_add_u32 v218, v218, 2, s0
	v_add_u32_e32 v219, 0xfffff059, v238
	v_med3_i32 v219, v219, s87, v240
	v_lshl_add_u32 v219, v219, 2, s0
	v_add_u32_e32 v220, 0xfffff05a, v238
	v_med3_i32 v220, v220, s87, v240
	v_lshl_add_u32 v220, v220, 2, s0
	v_add_u32_e32 v221, 0xfffff05b, v238
	v_med3_i32 v221, v221, s87, v240
	v_lshl_add_u32 v221, v221, 2, s0
	ds_read_b32 v206, v206 offset:512
	ds_read_b32 v207, v207 offset:512
	ds_read_b32 v208, v208 offset:512
	ds_read_b32 v209, v209 offset:512
	ds_read_b32 v210, v210 offset:512
	ds_read_b32 v211, v211 offset:512
	ds_read_b32 v212, v212 offset:512
	ds_read_b32 v213, v213 offset:512
	ds_read_b32 v214, v214 offset:512
	ds_read_b32 v215, v215 offset:512
	ds_read_b32 v216, v216 offset:512
	ds_read_b32 v217, v217 offset:512
	ds_read_b32 v218, v218 offset:512
	ds_read_b32 v219, v219 offset:512
	ds_read_b32 v220, v220 offset:512
	ds_read_b32 v221, v221 offset:512
	v_add_u32_e32 v0, 0xfffff060, v238
	v_med3_i32 v0, v0, s87, v240
	v_lshl_add_u32 v0, v0, 2, s0
	v_add_u32_e32 v1, 0xfffff061, v238
	v_med3_i32 v1, v1, s87, v240
	v_lshl_add_u32 v1, v1, 2, s0
	v_add_u32_e32 v2, 0xfffff062, v238
	v_med3_i32 v2, v2, s87, v240
	v_lshl_add_u32 v2, v2, 2, s0
	v_add_u32_e32 v3, 0xfffff063, v238
	v_med3_i32 v3, v3, s87, v240
	v_lshl_add_u32 v3, v3, 2, s0
	v_add_u32_e32 v4, 0xfffff068, v238
	v_med3_i32 v4, v4, s87, v240
	v_lshl_add_u32 v4, v4, 2, s0
	v_add_u32_e32 v5, 0xfffff069, v238
	v_med3_i32 v5, v5, s87, v240
	v_lshl_add_u32 v5, v5, 2, s0
	v_add_u32_e32 v6, 0xfffff06a, v238
	v_med3_i32 v6, v6, s87, v240
	v_lshl_add_u32 v6, v6, 2, s0
	v_add_u32_e32 v7, 0xfffff06b, v238
	v_med3_i32 v7, v7, s87, v240
	v_lshl_add_u32 v7, v7, 2, s0
	v_add_u32_e32 v8, 0xfffff070, v238
	v_med3_i32 v8, v8, s87, v240
	v_lshl_add_u32 v8, v8, 2, s0
	v_add_u32_e32 v9, 0xfffff071, v238
	v_med3_i32 v9, v9, s87, v240
	v_lshl_add_u32 v9, v9, 2, s0
	v_add_u32_e32 v10, 0xfffff072, v238
	v_med3_i32 v10, v10, s87, v240
	v_lshl_add_u32 v10, v10, 2, s0
	v_add_u32_e32 v11, 0xfffff073, v238
	v_med3_i32 v11, v11, s87, v240
	v_lshl_add_u32 v11, v11, 2, s0
	v_add_u32_e32 v12, 0xfffff078, v238
	v_med3_i32 v12, v12, s87, v240
	v_lshl_add_u32 v12, v12, 2, s0
	v_add_u32_e32 v13, 0xfffff079, v238
	v_med3_i32 v13, v13, s87, v240
	v_lshl_add_u32 v13, v13, 2, s0
	v_add_u32_e32 v14, 0xfffff07a, v238
	v_med3_i32 v14, v14, s87, v240
	v_lshl_add_u32 v14, v14, 2, s0
	v_add_u32_e32 v15, 0xfffff07b, v238
	v_med3_i32 v15, v15, s87, v240
	v_lshl_add_u32 v15, v15, 2, s0
	ds_read_b32 v0, v0 offset:512
	ds_read_b32 v1, v1 offset:512
	ds_read_b32 v2, v2 offset:512
	ds_read_b32 v3, v3 offset:512
	ds_read_b32 v4, v4 offset:512
	ds_read_b32 v5, v5 offset:512
	ds_read_b32 v6, v6 offset:512
	ds_read_b32 v7, v7 offset:512
	ds_read_b32 v8, v8 offset:512
	ds_read_b32 v9, v9 offset:512
	ds_read_b32 v10, v10 offset:512
	ds_read_b32 v11, v11 offset:512
	ds_read_b32 v12, v12 offset:512
	ds_read_b32 v13, v13 offset:512
	ds_read_b32 v14, v14 offset:512
	ds_read_b32 v15, v15 offset:512
	s_waitcnt lgkmcnt(0)
; #define LAS __attribute__((address_space(3)))
; __device__ __forceinline__ unsigned cvtpk(float lo, float hi) { f32x2_t v = {lo, hi}; bf16x2_t b = __builtin_convertvector(v, bf16x2_t); return __builtin_bit_cast(unsigned, b); }
; #define A_VLOAD(dst, d) do { const LAS char* vb_ = vbase + ((d) >> 1) * AVS + ((d) & 1) * 64; \
;         _Pragma("unroll") for (int ks = 0; ks < 4; ++ks) { const s16x4 vl_ = vtr(vb_ + (16 * ks) * AVP), vh_ = vtr(vb_ + (16 * ks + 8) * AVP); \
;             dst[ks] = (bf16x8){vl_[0], vl_[1], vl_[2], vl_[3], vh_[0], vh_[1], vh_[2], vh_[3]}; } } while (0)
; #define A_VMMA(src, d) do { _Pragma("unroll") for (int ks = 0; ks < 4; ++ks) o[d] = __builtin_amdgcn_mfma_f32_32x32x16_bf16(src[ks], pf[ks], o[d], 0, 0, 0); } while (0)
; __device__ __forceinline__ void attn_unit_A(const AttnP& P, int u, LAS char* lds) {
;     ...
;         const LAS char* vbase = lds + bcur + 2 * AKS + vrow * AVP + vcolb;
;     ...
;         bf16x8 vfa[4], vfb[4];
;         A_VLOAD(vfa, 0);
;         __builtin_amdgcn_sched_barrier(0);
;         float sacc = 0.f;
; #pragma unroll
;         for (int r = 0; r < 16; ++r) { sa0[r] = __builtin_amdgcn_exp2f(sa0[r]); sa1[r] = __builtin_amdgcn_exp2f(sa1[r]); sacc += sa0[r] + sa1[r]; }
;         lrun += sacc;
;         bf16x8 pf[4];
;         { u32x4 a;
;           a.x = cvtpk(sa0[0], sa0[1]); a.y = cvtpk(sa0[2], sa0[3]); a.z = cvtpk(sa0[4], sa0[5]); a.w = cvtpk(sa0[6], sa0[7]); pf[0] = __builtin_bit_cast(bf16x8, a);
;           a.x = cvtpk(sa0[8], sa0[9]); a.y = cvtpk(sa0[10], sa0[11]); a.z = cvtpk(sa0[12], sa0[13]); a.w = cvtpk(sa0[14], sa0[15]); pf[1] = __builtin_bit_cast(bf16x8, a);
;           a.x = cvtpk(sa1[0], sa1[1]); a.y = cvtpk(sa1[2], sa1[3]); a.z = cvtpk(sa1[4], sa1[5]); a.w = cvtpk(sa1[6], sa1[7]); pf[2] = __builtin_bit_cast(bf16x8, a);
;           a.x = cvtpk(sa1[8], sa1[9]); a.y = cvtpk(sa1[10], sa1[11]); a.z = cvtpk(sa1[12], sa1[13]); a.w = cvtpk(sa1[14], sa1[15]); pf[3] = __builtin_bit_cast(bf16x8, a); }
;         __builtin_amdgcn_sched_barrier(0);
;         A_VLOAD(vfb, 1);
;         __builtin_amdgcn_sched_barrier(0);
;         A_VMMA(vfa, 0);
;         A_VLOAD(vfa, 2);
;         __builtin_amdgcn_sched_barrier(0);
;         A_VMMA(vfb, 1);
;         A_VLOAD(vfb, 3);
;         __builtin_amdgcn_sched_barrier(0);
;         A_VMMA(vfa, 2);
;         __builtin_amdgcn_sched_barrier(0);
;         A_VMMA(vfb, 3);
	v_add_f32_e32 v206, v206, v80
	v_add_f32_e32 v207, v207, v80
	v_add_f32_e32 v208, v208, v80
	v_add_f32_e32 v209, v209, v80
	v_add_f32_e32 v210, v210, v80
	v_add_f32_e32 v211, v211, v80
	v_add_f32_e32 v212, v212, v80
	v_add_f32_e32 v213, v213, v80
	v_add_f32_e32 v214, v214, v80
	v_add_f32_e32 v215, v215, v80
	v_add_f32_e32 v216, v216, v80
	v_add_f32_e32 v217, v217, v80
	v_add_f32_e32 v218, v218, v80
	v_add_f32_e32 v219, v219, v80
	v_add_f32_e32 v220, v220, v80
	v_add_f32_e32 v221, v221, v80
	v_add_f32_e32 v0, v0, v80
	v_add_f32_e32 v1, v1, v80
	v_add_f32_e32 v2, v2, v80
	v_add_f32_e32 v3, v3, v80
	v_add_f32_e32 v4, v4, v80
	v_add_f32_e32 v5, v5, v80
	v_add_f32_e32 v6, v6, v80
	v_add_f32_e32 v7, v7, v80
	v_add_f32_e32 v8, v8, v80
	v_add_f32_e32 v9, v9, v80
	v_add_f32_e32 v10, v10, v80
	v_add_f32_e32 v11, v11, v80
	v_add_f32_e32 v12, v12, v80
	v_add_f32_e32 v13, v13, v80
	v_add_f32_e32 v14, v14, v80
	v_add_f32_e32 v15, v15, v80
	ds_read_b128 v[178:181], v244
	ds_read_b128 v[182:185], v244 offset:4608
	ds_read_b128 v[186:189], v244 offset:32
	ds_read_b128 v[190:193], v244 offset:4640
	ds_read_b128 v[222:225], v244 offset:64
	ds_read_b128 v[226:229], v244 offset:4672
	ds_read_b128 v[230:233], v244 offset:96
	v_exp_f32_e32 v96, v96
	v_exp_f32_e32 v97, v97
	v_exp_f32_e32 v98, v98
	v_exp_f32_e32 v99, v99
	s_waitcnt lgkmcnt(6)
	v_mfma_f32_32x32x16_bf16 v[206:221], v[178:181], v[140:143], v[206:221]
	ds_read_b128 v[178:181], v244 offset:4704
	v_exp_f32_e32 v100, v100
	v_exp_f32_e32 v101, v101
	v_add_f32_e32 v173, v173, v96
	v_add_f32_e32 v202, v202, v97
	s_waitcnt lgkmcnt(6)
	v_mfma_f32_32x32x16_bf16 v[0:15], v[182:185], v[140:143], v[0:15]
	ds_read_b64_tr_b16 v[182:183], v235 offset:18432
	ds_read_b64_tr_b16 v[184:185], v235 offset:19968
	v_exp_f32_e32 v102, v102
	v_exp_f32_e32 v103, v103
	v_add_f32_e32 v173, v173, v98
	v_add_f32_e32 v202, v202, v99
.Latt2_o_join:
	s_waitcnt lgkmcnt(7)
	v_mfma_f32_32x32x16_bf16 v[206:221], v[186:189], v[136:139], v[206:221]
	ds_read_b64_tr_b16 v[186:187], v235 offset:18496
	ds_read_b64_tr_b16 v[188:189], v235 offset:20032
	v_add_f32_e32 v173, v173, v100
	v_add_f32_e32 v202, v202, v101
	v_add_f32_e32 v173, v173, v102
	v_add_f32_e32 v202, v202, v103
	v_exp_f32_e32 v104, v104
	s_waitcnt lgkmcnt(8)
	v_mfma_f32_32x32x16_bf16 v[0:15], v[190:193], v[136:139], v[0:15]
	ds_read_b64_tr_b16 v[190:191], v235 offset:30720
	ds_read_b64_tr_b16 v[192:193], v235 offset:32256
	v_cvt_pk_bf16_f32 v96, v96, v97
	v_cvt_pk_bf16_f32 v97, v98, v99
	v_cvt_pk_bf16_f32 v98, v100, v101
	v_cvt_pk_bf16_f32 v99, v102, v103
	v_exp_f32_e32 v105, v105
	s_waitcnt lgkmcnt(9)
	v_mfma_f32_32x32x16_bf16 v[206:221], v[222:225], v[132:135], v[206:221]
	ds_read_b64_tr_b16 v[222:223], v235 offset:30784
	ds_read_b64_tr_b16 v[224:225], v235 offset:32320
	v_exp_f32_e32 v106, v106
	v_exp_f32_e32 v107, v107
	v_exp_f32_e32 v108, v108
	s_waitcnt lgkmcnt(10)
	v_mfma_f32_32x32x16_bf16 v[0:15], v[226:229], v[132:135], v[0:15]
	ds_read_b64_tr_b16 v[226:227], v235 offset:21504
	ds_read_b64_tr_b16 v[228:229], v235 offset:23040
	v_exp_f32_e32 v109, v109
	v_exp_f32_e32 v110, v110
	v_exp_f32_e32 v111, v111
	s_waitcnt lgkmcnt(11)
	v_mfma_f32_32x32x16_bf16 v[206:221], v[230:233], v[128:131], v[206:221]
	ds_read_b64_tr_b16 v[230:231], v235 offset:21568
	ds_read_b64_tr_b16 v[232:233], v235 offset:23104
	v_add_f32_e32 v173, v173, v104
	v_add_f32_e32 v202, v202, v105
	v_add_f32_e32 v173, v173, v106
	v_add_f32_e32 v202, v202, v107
	v_add_f32_e32 v173, v173, v108
	v_add_f32_e32 v202, v202, v109
	s_waitcnt lgkmcnt(12)
	v_mfma_f32_32x32x16_bf16 v[0:15], v[178:181], v[128:131], v[0:15]
	ds_read_b64_tr_b16 v[178:179], v235 offset:33792
	ds_read_b64_tr_b16 v[180:181], v235 offset:35328
	v_add_f32_e32 v173, v173, v110
	v_add_f32_e32 v202, v202, v111
	v_cvt_pk_bf16_f32 v100, v104, v105
	v_cvt_pk_bf16_f32 v101, v106, v107
	v_cvt_pk_bf16_f32 v102, v108, v109
	v_cvt_pk_bf16_f32 v103, v110, v111
	s_waitcnt lgkmcnt(12)
	v_mfma_f32_32x32x16_bf16 v[64:79], v[182:185], v[96:99], v[64:79]
	ds_read_b64_tr_b16 v[182:183], v235 offset:33856
	ds_read_b64_tr_b16 v[184:185], v235 offset:35392
	v_exp_f32_e32 v112, v112
	v_exp_f32_e32 v113, v113
	v_exp_f32_e32 v114, v114
	s_waitcnt lgkmcnt(12)
	v_mfma_f32_32x32x16_bf16 v[48:63], v[186:189], v[96:99], v[48:63]
	ds_read_b64_tr_b16 v[186:187], v235 offset:24576
	ds_read_b64_tr_b16 v[188:189], v235 offset:26112
	v_exp_f32_e32 v115, v115
	v_exp_f32_e32 v116, v116
	v_exp_f32_e32 v117, v117
	s_waitcnt lgkmcnt(12)
	v_mfma_f32_32x32x16_bf16 v[32:47], v[190:193], v[96:99], v[32:47]
	ds_read_b64_tr_b16 v[190:191], v235 offset:24640
	ds_read_b64_tr_b16 v[192:193], v235 offset:26176
	v_exp_f32_e32 v118, v118
	v_exp_f32_e32 v119, v119
	v_add_f32_e32 v173, v173, v112
	v_add_f32_e32 v202, v202, v113
	s_waitcnt lgkmcnt(12)
	v_mfma_f32_32x32x16_bf16 v[16:31], v[222:225], v[96:99], v[16:31]
	ds_read_b64_tr_b16 v[222:223], v235 offset:36864
	ds_read_b64_tr_b16 v[224:225], v235 offset:38400
	v_add_f32_e32 v173, v173, v114
	v_add_f32_e32 v202, v202, v115
	v_add_f32_e32 v173, v173, v116
	v_add_f32_e32 v202, v202, v117
	v_add_f32_e32 v173, v173, v118
	v_add_f32_e32 v202, v202, v119
	s_waitcnt lgkmcnt(12)
	v_mfma_f32_32x32x16_bf16 v[64:79], v[226:229], v[100:103], v[64:79]
	ds_read_b64_tr_b16 v[226:227], v235 offset:36928
	ds_read_b64_tr_b16 v[228:229], v235 offset:38464
	v_cvt_pk_bf16_f32 v104, v112, v113
	v_cvt_pk_bf16_f32 v105, v114, v115
	v_cvt_pk_bf16_f32 v106, v116, v117
	v_cvt_pk_bf16_f32 v107, v118, v119
	v_exp_f32_e32 v120, v120
	s_waitcnt lgkmcnt(12)
; __device__ __forceinline__ unsigned cvtpk(float lo, float hi) { f32x2_t v = {lo, hi}; bf16x2_t b = __builtin_convertvector(v, bf16x2_t); return __builtin_bit_cast(unsigned, b); }
; #define A_BAR() asm volatile("s_waitcnt lgkmcnt(0)\n\ts_barrier" ::: "memory")
; __device__ __forceinline__ void attn_unit_A(const AttnP& P, int u, LAS char* lds) {
;     ...
;         float sacc = 0.f;
; #pragma unroll
;         for (int r = 0; r < 16; ++r) { sa0[r] = __builtin_amdgcn_exp2f(sa0[r]); sa1[r] = __builtin_amdgcn_exp2f(sa1[r]); sacc += sa0[r] + sa1[r]; }
;         lrun += sacc;
;         bf16x8 pf[4];
;         { u32x4 a;
;           a.x = cvtpk(sa0[0], sa0[1]); a.y = cvtpk(sa0[2], sa0[3]); a.z = cvtpk(sa0[4], sa0[5]); a.w = cvtpk(sa0[6], sa0[7]); pf[0] = __builtin_bit_cast(bf16x8, a);
;           a.x = cvtpk(sa0[8], sa0[9]); a.y = cvtpk(sa0[10], sa0[11]); a.z = cvtpk(sa0[12], sa0[13]); a.w = cvtpk(sa0[14], sa0[15]); pf[1] = __builtin_bit_cast(bf16x8, a);
;           a.x = cvtpk(sa1[0], sa1[1]); a.y = cvtpk(sa1[2], sa1[3]); a.z = cvtpk(sa1[4], sa1[5]); a.w = cvtpk(sa1[6], sa1[7]); pf[2] = __builtin_bit_cast(bf16x8, a);
;           a.x = cvtpk(sa1[8], sa1[9]); a.y = cvtpk(sa1[10], sa1[11]); a.z = cvtpk(sa1[12], sa1[13]); a.w = cvtpk(sa1[14], sa1[15]); pf[3] = __builtin_bit_cast(bf16x8, a); }
;         __builtin_amdgcn_sched_barrier(0);
;         A_VLOAD(vfb, 1);
;         __builtin_amdgcn_sched_barrier(0);
;         A_VMMA(vfa, 0);
;         A_VLOAD(vfa, 2);
;         __builtin_amdgcn_sched_barrier(0);
;         A_VMMA(vfb, 1);
;         A_VLOAD(vfb, 3);
;         __builtin_amdgcn_sched_barrier(0);
;         A_VMMA(vfa, 2);
;         __builtin_amdgcn_sched_barrier(0);
;         A_VMMA(vfb, 3);
;     ...
;         __builtin_amdgcn_sched_barrier(0); A_BAR(); A_QKBLK();
;     ...
;         if (more) {
;             if (clsn == 1) A_NEAR(sa0, sa1, t + 1);
;             float mx_; A_ROWMAX(sa0, sa1, mx_);
;             if (__any(mx_ > 8.0f)) { const float dl = fmaxf(mx_, 0.f); const float f_ = __builtin_amdgcn_exp2f(-dl); lrun *= f_;
; #pragma unroll
;                 for (int r = 0; r < 16; ++r) { sa0[r] -= dl; sa1[r] -= dl; negc[r] -= dl; }
; #pragma unroll
;                 for (int d = 0; d < 4; ++d)
; #pragma unroll
;                     for (int r = 0; r < 16; ++r) o[d][r] *= f_; }
;         }
	v_mfma_f32_32x32x16_bf16 v[48:63], v[230:233], v[100:103], v[48:63]
	ds_read_b64_tr_b16 v[230:231], v235 offset:27648
	ds_read_b64_tr_b16 v[232:233], v235 offset:29184
	v_exp_f32_e32 v121, v121
	v_exp_f32_e32 v122, v122
	v_exp_f32_e32 v123, v123
	s_waitcnt lgkmcnt(12)
	v_mfma_f32_32x32x16_bf16 v[32:47], v[178:181], v[100:103], v[32:47]
	ds_read_b64_tr_b16 v[178:179], v235 offset:27712
	ds_read_b64_tr_b16 v[180:181], v235 offset:29248
	v_exp_f32_e32 v124, v124
	v_exp_f32_e32 v125, v125
	v_exp_f32_e32 v126, v126
	s_waitcnt lgkmcnt(12)
	v_mfma_f32_32x32x16_bf16 v[16:31], v[182:185], v[100:103], v[16:31]
	ds_read_b64_tr_b16 v[182:183], v235 offset:39936
	ds_read_b64_tr_b16 v[184:185], v235 offset:41472
	v_exp_f32_e32 v127, v127
	v_add_f32_e32 v173, v173, v120
	v_add_f32_e32 v202, v202, v121
	v_add_f32_e32 v173, v173, v122
	v_add_f32_e32 v202, v202, v123
	s_waitcnt lgkmcnt(12)
	v_mfma_f32_32x32x16_bf16 v[64:79], v[186:189], v[104:107], v[64:79]
	ds_read_b64_tr_b16 v[186:187], v235 offset:40000
	ds_read_b64_tr_b16 v[188:189], v235 offset:41536
	v_add_f32_e32 v173, v173, v124
	v_add_f32_e32 v202, v202, v125
	v_add_f32_e32 v173, v173, v126
	v_add_f32_e32 v202, v202, v127
	v_max3_f32 v243, v206, v207, v208
	s_waitcnt lgkmcnt(12)
	v_mfma_f32_32x32x16_bf16 v[48:63], v[190:193], v[104:107], v[48:63]
	v_cvt_pk_bf16_f32 v108, v120, v121
	v_cvt_pk_bf16_f32 v109, v122, v123
	v_cvt_pk_bf16_f32 v110, v124, v125
	v_cvt_pk_bf16_f32 v111, v126, v127
	v_max3_f32 v239, v0, v1, v2
	v_max3_f32 v243, v243, v209, v210
	s_waitcnt lgkmcnt(10)
	v_mfma_f32_32x32x16_bf16 v[32:47], v[222:225], v[104:107], v[32:47]
	v_max3_f32 v239, v239, v3, v4
	v_max3_f32 v243, v243, v211, v212
	v_max3_f32 v239, v239, v5, v6
	v_max3_f32 v243, v243, v213, v214
	v_max3_f32 v239, v239, v7, v8
	v_max3_f32 v243, v243, v215, v216
	v_max3_f32 v239, v239, v9, v10
	v_max3_f32 v243, v243, v217, v218
	v_max3_f32 v239, v239, v11, v12
	v_max3_f32 v243, v243, v219, v220
	v_max3_f32 v239, v239, v13, v14
	v_max_f32_e32 v243, v243, v221
	v_max_f32_e32 v239, v239, v15
	v_max_f32_e32 v243, v243, v239
	s_waitcnt lgkmcnt(8)
	v_mfma_f32_32x32x16_bf16 v[16:31], v[226:229], v[104:107], v[16:31]
	s_waitcnt vmcnt(0)
	v_add3_u32 v238, s35, v172, v160
	v_add3_u32 v239, s35, v174, v160
	ds_write_b128 v238, v[156:159]
	ds_write_b128 v238, v[152:155] offset:9216
	s_waitcnt lgkmcnt(8)
	v_mfma_f32_32x32x16_bf16 v[64:79], v[230:233], v[108:111], v[64:79]
	ds_write_b128 v239, v[148:151] offset:18432
	ds_write_b128 v239, v[144:147] offset:30720
	v_mov_b32_e32 v239, v243
	s_min_i32 s0, s30, 0xf80
	v_add_u32_e32 v238, s0, v175
	v_min_i32_e32 v238, 0x100f, v238
	s_waitcnt lgkmcnt(8)
	v_mfma_f32_32x32x16_bf16 v[48:63], v[178:181], v[108:111], v[48:63]
	v_permlane32_swap_b32_e32 v243, v239
	v_mad_i64_i32 v[244:245], s[0:1], v238, s51, v[162:163]
	global_load_dwordx4 v[156:159], v[244:245], off offset:1024
	global_load_dwordx4 v[152:155], v[244:245], off offset:1152
	s_waitcnt lgkmcnt(6)
	v_mfma_f32_32x32x16_bf16 v[32:47], v[182:185], v[108:111], v[32:47]
	global_load_dwordx4 v[148:151], v[244:245], off offset:2048
	global_load_dwordx4 v[144:147], v[244:245], off offset:2176
	v_max_f32_e32 v243, v243, v239
	s_waitcnt lgkmcnt(4)
	v_mfma_f32_32x32x16_bf16 v[16:31], v[186:189], v[108:111], v[16:31]
	s_mov_b32 s34, s29
	s_mov_b32 s26, s28
	s_mov_b32 s28, s35
	s_add_i32 s0, s35, 0xa800
	s_cmp_lg_u32 s0, 0x1f800
	s_cselect_b32 s35, s0, 0
	s_mov_b32 s31, s30
	v_cmp_lt_f32_e32 vcc, s10, v243
	s_cbranch_vccz .Latt2_o_noresc
	s_nop 11
	v_max_f32_e32 v243, 0, v243
	v_exp_f32_e64 v244, -v243
	v_sub_f32_e32 v80, v80, v243
	v_sub_f32_e32 v81, v81, v243
	v_sub_f32_e32 v82, v82, v243
	v_sub_f32_e32 v83, v83, v243
	v_sub_f32_e32 v84, v84, v243
	v_sub_f32_e32 v85, v85, v243
	v_sub_f32_e32 v86, v86, v243
	v_sub_f32_e32 v87, v87, v243
	v_sub_f32_e32 v88, v88, v243
	v_sub_f32_e32 v89, v89, v243
	v_sub_f32_e32 v90, v90, v243
	v_sub_f32_e32 v91, v91, v243
	v_sub_f32_e32 v92, v92, v243
	v_sub_f32_e32 v93, v93, v243
	v_sub_f32_e32 v94, v94, v243
	v_sub_f32_e32 v95, v95, v243
	v_sub_f32_e32 v206, v206, v243
	v_sub_f32_e32 v207, v207, v243
	v_sub_f32_e32 v208, v208, v243
	v_sub_f32_e32 v209, v209, v243
	v_sub_f32_e32 v210, v210, v243
	v_sub_f32_e32 v211, v211, v243
	v_sub_f32_e32 v212, v212, v243
	v_sub_f32_e32 v213, v213, v243
	v_sub_f32_e32 v214, v214, v243
	v_sub_f32_e32 v215, v215, v243
	v_sub_f32_e32 v216, v216, v243
	v_sub_f32_e32 v217, v217, v243
	v_sub_f32_e32 v218, v218, v243
	v_sub_f32_e32 v219, v219, v243
	v_sub_f32_e32 v220, v220, v243
	v_sub_f32_e32 v221, v221, v243
	v_sub_f32_e32 v0, v0, v243
	v_sub_f32_e32 v1, v1, v243
	v_sub_f32_e32 v2, v2, v243
	v_sub_f32_e32 v3, v3, v243
	v_sub_f32_e32 v4, v4, v243
	v_sub_f32_e32 v5, v5, v243
	v_sub_f32_e32 v6, v6, v243
	v_sub_f32_e32 v7, v7, v243
	v_sub_f32_e32 v8, v8, v243
	v_sub_f32_e32 v9, v9, v243
	v_sub_f32_e32 v10, v10, v243
	v_sub_f32_e32 v11, v11, v243
	v_sub_f32_e32 v12, v12, v243
	v_sub_f32_e32 v13, v13, v243
	v_sub_f32_e32 v14, v14, v243
	v_sub_f32_e32 v15, v15, v243
	v_pk_mul_f32 v[64:65], v[64:65], v[244:245] op_sel_hi:[1,0]
	v_pk_mul_f32 v[66:67], v[66:67], v[244:245] op_sel_hi:[1,0]
	v_pk_mul_f32 v[68:69], v[68:69], v[244:245] op_sel_hi:[1,0]
	v_pk_mul_f32 v[70:71], v[70:71], v[244:245] op_sel_hi:[1,0]
	v_pk_mul_f32 v[72:73], v[72:73], v[244:245] op_sel_hi:[1,0]
	v_pk_mul_f32 v[74:75], v[74:75], v[244:245] op_sel_hi:[1,0]
	v_pk_mul_f32 v[76:77], v[76:77], v[244:245] op_sel_hi:[1,0]
	v_pk_mul_f32 v[78:79], v[78:79], v[244:245] op_sel_hi:[1,0]
	v_pk_mul_f32 v[48:49], v[48:49], v[244:245] op_sel_hi:[1,0]
	v_pk_mul_f32 v[50:51], v[50:51], v[244:245] op_sel_hi:[1,0]
	v_pk_mul_f32 v[52:53], v[52:53], v[244:245] op_sel_hi:[1,0]
	v_pk_mul_f32 v[54:55], v[54:55], v[244:245] op_sel_hi:[1,0]
	v_pk_mul_f32 v[56:57], v[56:57], v[244:245] op_sel_hi:[1,0]
	v_pk_mul_f32 v[58:59], v[58:59], v[244:245] op_sel_hi:[1,0]
	v_pk_mul_f32 v[60:61], v[60:61], v[244:245] op_sel_hi:[1,0]
	v_pk_mul_f32 v[62:63], v[62:63], v[244:245] op_sel_hi:[1,0]
	v_pk_mul_f32 v[32:33], v[32:33], v[244:245] op_sel_hi:[1,0]
	v_pk_mul_f32 v[34:35], v[34:35], v[244:245] op_sel_hi:[1,0]
	v_pk_mul_f32 v[36:37], v[36:37], v[244:245] op_sel_hi:[1,0]
	v_pk_mul_f32 v[38:39], v[38:39], v[244:245] op_sel_hi:[1,0]
	v_pk_mul_f32 v[40:41], v[40:41], v[244:245] op_sel_hi:[1,0]
	v_pk_mul_f32 v[42:43], v[42:43], v[244:245] op_sel_hi:[1,0]
	v_pk_mul_f32 v[44:45], v[44:45], v[244:245] op_sel_hi:[1,0]
	v_pk_mul_f32 v[46:47], v[46:47], v[244:245] op_sel_hi:[1,0]
	v_pk_mul_f32 v[16:17], v[16:17], v[244:245] op_sel_hi:[1,0]
	v_pk_mul_f32 v[18:19], v[18:19], v[244:245] op_sel_hi:[1,0]
	v_pk_mul_f32 v[20:21], v[20:21], v[244:245] op_sel_hi:[1,0]
	v_pk_mul_f32 v[22:23], v[22:23], v[244:245] op_sel_hi:[1,0]
	v_pk_mul_f32 v[24:25], v[24:25], v[244:245] op_sel_hi:[1,0]
	v_pk_mul_f32 v[26:27], v[26:27], v[244:245] op_sel_hi:[1,0]
	v_pk_mul_f32 v[28:29], v[28:29], v[244:245] op_sel_hi:[1,0]
	v_pk_mul_f32 v[30:31], v[30:31], v[244:245] op_sel_hi:[1,0]
	v_mul_f32_e32 v173, v173, v244
	v_mul_f32_e32 v202, v202, v244
	s_nop 1
